# lever 1 on the inter-chunk state scan: software-pipelined (group g+1 loaded before group g is processed, counted vmcnt waits that do not wait for the in-place stores) instead of several vmcnt(0) per 8
# speedup vs baseline: 1.0034x; 1.0007x over previous
.LBB0_484:
	v_add_u32_e32 v0, 0xdcd1000, v0
	v_add_u32_e32 v2, 0xcd0000, v2
	s_mov_b64 s[100:101], s[58:59]
	s_mov_b64 s[98:99], s[58:59]
	global_load_dwordx4 v[44:47], v0, s[100:101]
	s_add_u32 s100, s100, 0x8100
	s_addc_u32 s101, s101, 0
	global_load_dwordx4 v[48:51], v0, s[100:101]
	s_add_u32 s100, s100, 0x8100
	s_addc_u32 s101, s101, 0
	global_load_dwordx4 v[52:55], v0, s[100:101]
	s_add_u32 s100, s100, 0x8100
	s_addc_u32 s101, s101, 0
	global_load_dwordx4 v[56:59], v0, s[100:101]
	s_add_u32 s100, s100, 0x8100
	s_addc_u32 s101, s101, 0
	global_load_dwordx4 v[60:63], v0, s[100:101]
	s_add_u32 s100, s100, 0x8100
	s_addc_u32 s101, s101, 0
	global_load_dwordx4 v[64:67], v0, s[100:101]
	s_add_u32 s100, s100, 0x8100
	s_addc_u32 s101, s101, 0
	global_load_dwordx4 v[68:71], v0, s[100:101]
	s_add_u32 s100, s100, 0x8100
	s_addc_u32 s101, s101, 0
	global_load_dwordx4 v[72:75], v0, s[100:101]
	s_add_u32 s100, s100, 0x8100
	s_addc_u32 s101, s101, 0
	global_load_dword v108, v2, s[58:59]
	global_load_dword v109, v2, s[58:59] offset:4
	global_load_dword v110, v2, s[58:59] offset:8
	global_load_dword v111, v2, s[58:59] offset:12
	global_load_dword v112, v2, s[58:59] offset:16
	global_load_dword v113, v2, s[58:59] offset:20
	global_load_dword v114, v2, s[58:59] offset:24
	global_load_dword v115, v2, s[58:59] offset:28
	global_load_dwordx4 v[76:79], v0, s[100:101]
	s_add_u32 s100, s100, 0x8100
	s_addc_u32 s101, s101, 0
	global_load_dwordx4 v[80:83], v0, s[100:101]
	s_add_u32 s100, s100, 0x8100
	s_addc_u32 s101, s101, 0
	global_load_dwordx4 v[84:87], v0, s[100:101]
	s_add_u32 s100, s100, 0x8100
	s_addc_u32 s101, s101, 0
	global_load_dwordx4 v[88:91], v0, s[100:101]
	s_add_u32 s100, s100, 0x8100
	s_addc_u32 s101, s101, 0
	global_load_dwordx4 v[92:95], v0, s[100:101]
	s_add_u32 s100, s100, 0x8100
	s_addc_u32 s101, s101, 0
	global_load_dwordx4 v[96:99], v0, s[100:101]
	s_add_u32 s100, s100, 0x8100
	s_addc_u32 s101, s101, 0
	global_load_dwordx4 v[100:103], v0, s[100:101]
	s_add_u32 s100, s100, 0x8100
	s_addc_u32 s101, s101, 0
	global_load_dwordx4 v[104:107], v0, s[100:101]
	s_add_u32 s100, s100, 0x8100
	s_addc_u32 s101, s101, 0
	global_load_dword v116, v2, s[58:59] offset:32
	global_load_dword v117, v2, s[58:59] offset:36
	global_load_dword v118, v2, s[58:59] offset:40
	global_load_dword v119, v2, s[58:59] offset:44
	global_load_dword v120, v2, s[58:59] offset:48
	global_load_dword v121, v2, s[58:59] offset:52
	global_load_dword v122, v2, s[58:59] offset:56
	global_load_dword v123, v2, s[58:59] offset:60
	s_waitcnt vmcnt(16)
	v_cvt_pk_bf16_f32 v124, v8, v9
	v_cvt_pk_bf16_f32 v125, v10, v11
	v_cvt_pk_bf16_f32 v126, v12, v13
	v_cvt_pk_bf16_f32 v127, v14, v15
	v_mul_f32_e32 v128, 0x3fb8aa3b, v108
	v_exp_f32_e32 v128, v128
	global_store_dwordx4 v0, v[124:127], s[98:99]
	s_add_u32 s98, s98, 0x8100
	s_addc_u32 s99, s99, 0
	v_lshlrev_b32_e32 v130, 16, v44
	v_and_b32_e32 v131, 0xffff0000, v44
	v_lshlrev_b32_e32 v132, 16, v45
	v_and_b32_e32 v133, 0xffff0000, v45
	v_lshlrev_b32_e32 v134, 16, v46
	v_and_b32_e32 v135, 0xffff0000, v46
	v_lshlrev_b32_e32 v136, 16, v47
	v_and_b32_e32 v137, 0xffff0000, v47
	v_pk_fma_f32 v[8:9], v[8:9], v[128:129], v[130:131] op_sel_hi:[1,0,1]
	v_pk_fma_f32 v[10:11], v[10:11], v[128:129], v[132:133] op_sel_hi:[1,0,1]
	v_pk_fma_f32 v[12:13], v[12:13], v[128:129], v[134:135] op_sel_hi:[1,0,1]
	v_pk_fma_f32 v[14:15], v[14:15], v[128:129], v[136:137] op_sel_hi:[1,0,1]
	v_cvt_pk_bf16_f32 v124, v8, v9
	v_cvt_pk_bf16_f32 v125, v10, v11
	v_cvt_pk_bf16_f32 v126, v12, v13
	v_cvt_pk_bf16_f32 v127, v14, v15
	v_mul_f32_e32 v128, 0x3fb8aa3b, v109
	v_exp_f32_e32 v128, v128
	global_store_dwordx4 v0, v[124:127], s[98:99]
	s_add_u32 s98, s98, 0x8100
	s_addc_u32 s99, s99, 0
	v_lshlrev_b32_e32 v130, 16, v48
	v_and_b32_e32 v131, 0xffff0000, v48
	v_lshlrev_b32_e32 v132, 16, v49
	v_and_b32_e32 v133, 0xffff0000, v49
	v_lshlrev_b32_e32 v134, 16, v50
	v_and_b32_e32 v135, 0xffff0000, v50
	v_lshlrev_b32_e32 v136, 16, v51
	v_and_b32_e32 v137, 0xffff0000, v51
	v_pk_fma_f32 v[8:9], v[8:9], v[128:129], v[130:131] op_sel_hi:[1,0,1]
	v_pk_fma_f32 v[10:11], v[10:11], v[128:129], v[132:133] op_sel_hi:[1,0,1]
	v_pk_fma_f32 v[12:13], v[12:13], v[128:129], v[134:135] op_sel_hi:[1,0,1]
	v_pk_fma_f32 v[14:15], v[14:15], v[128:129], v[136:137] op_sel_hi:[1,0,1]
	v_cvt_pk_bf16_f32 v124, v8, v9
	v_cvt_pk_bf16_f32 v125, v10, v11
	v_cvt_pk_bf16_f32 v126, v12, v13
	v_cvt_pk_bf16_f32 v127, v14, v15
	v_mul_f32_e32 v128, 0x3fb8aa3b, v110
	v_exp_f32_e32 v128, v128
	global_store_dwordx4 v0, v[124:127], s[98:99]
	s_add_u32 s98, s98, 0x8100
	s_addc_u32 s99, s99, 0
	v_lshlrev_b32_e32 v130, 16, v52
	v_and_b32_e32 v131, 0xffff0000, v52
	v_lshlrev_b32_e32 v132, 16, v53
	v_and_b32_e32 v133, 0xffff0000, v53
	v_lshlrev_b32_e32 v134, 16, v54
	v_and_b32_e32 v135, 0xffff0000, v54
	v_lshlrev_b32_e32 v136, 16, v55
	v_and_b32_e32 v137, 0xffff0000, v55
	v_pk_fma_f32 v[8:9], v[8:9], v[128:129], v[130:131] op_sel_hi:[1,0,1]
	v_pk_fma_f32 v[10:11], v[10:11], v[128:129], v[132:133] op_sel_hi:[1,0,1]
	v_pk_fma_f32 v[12:13], v[12:13], v[128:129], v[134:135] op_sel_hi:[1,0,1]
	v_pk_fma_f32 v[14:15], v[14:15], v[128:129], v[136:137] op_sel_hi:[1,0,1]
	v_cvt_pk_bf16_f32 v124, v8, v9
	v_cvt_pk_bf16_f32 v125, v10, v11
	v_cvt_pk_bf16_f32 v126, v12, v13
	v_cvt_pk_bf16_f32 v127, v14, v15
	v_mul_f32_e32 v128, 0x3fb8aa3b, v111
	v_exp_f32_e32 v128, v128
	global_store_dwordx4 v0, v[124:127], s[98:99]
	s_add_u32 s98, s98, 0x8100
	s_addc_u32 s99, s99, 0
	v_lshlrev_b32_e32 v130, 16, v56
	v_and_b32_e32 v131, 0xffff0000, v56
	v_lshlrev_b32_e32 v132, 16, v57
	v_and_b32_e32 v133, 0xffff0000, v57
	v_lshlrev_b32_e32 v134, 16, v58
	v_and_b32_e32 v135, 0xffff0000, v58
	v_lshlrev_b32_e32 v136, 16, v59
	v_and_b32_e32 v137, 0xffff0000, v59
	v_pk_fma_f32 v[8:9], v[8:9], v[128:129], v[130:131] op_sel_hi:[1,0,1]
	v_pk_fma_f32 v[10:11], v[10:11], v[128:129], v[132:133] op_sel_hi:[1,0,1]
	v_pk_fma_f32 v[12:13], v[12:13], v[128:129], v[134:135] op_sel_hi:[1,0,1]
	v_pk_fma_f32 v[14:15], v[14:15], v[128:129], v[136:137] op_sel_hi:[1,0,1]
	v_cvt_pk_bf16_f32 v124, v8, v9
	v_cvt_pk_bf16_f32 v125, v10, v11
	v_cvt_pk_bf16_f32 v126, v12, v13
	v_cvt_pk_bf16_f32 v127, v14, v15
	v_mul_f32_e32 v128, 0x3fb8aa3b, v112
	v_exp_f32_e32 v128, v128
	global_store_dwordx4 v0, v[124:127], s[98:99]
	s_add_u32 s98, s98, 0x8100
	s_addc_u32 s99, s99, 0
	v_lshlrev_b32_e32 v130, 16, v60
	v_and_b32_e32 v131, 0xffff0000, v60
	v_lshlrev_b32_e32 v132, 16, v61
	v_and_b32_e32 v133, 0xffff0000, v61
	v_lshlrev_b32_e32 v134, 16, v62
	v_and_b32_e32 v135, 0xffff0000, v62
	v_lshlrev_b32_e32 v136, 16, v63
	v_and_b32_e32 v137, 0xffff0000, v63
	v_pk_fma_f32 v[8:9], v[8:9], v[128:129], v[130:131] op_sel_hi:[1,0,1]
	v_pk_fma_f32 v[10:11], v[10:11], v[128:129], v[132:133] op_sel_hi:[1,0,1]
	v_pk_fma_f32 v[12:13], v[12:13], v[128:129], v[134:135] op_sel_hi:[1,0,1]
	v_pk_fma_f32 v[14:15], v[14:15], v[128:129], v[136:137] op_sel_hi:[1,0,1]
	v_cvt_pk_bf16_f32 v124, v8, v9
	v_cvt_pk_bf16_f32 v125, v10, v11
	v_cvt_pk_bf16_f32 v126, v12, v13
	v_cvt_pk_bf16_f32 v127, v14, v15
	v_mul_f32_e32 v128, 0x3fb8aa3b, v113
	v_exp_f32_e32 v128, v128
	global_store_dwordx4 v0, v[124:127], s[98:99]
	s_add_u32 s98, s98, 0x8100
	s_addc_u32 s99, s99, 0
	v_lshlrev_b32_e32 v130, 16, v64
	v_and_b32_e32 v131, 0xffff0000, v64
	v_lshlrev_b32_e32 v132, 16, v65
	v_and_b32_e32 v133, 0xffff0000, v65
	v_lshlrev_b32_e32 v134, 16, v66
	v_and_b32_e32 v135, 0xffff0000, v66
	v_lshlrev_b32_e32 v136, 16, v67
	v_and_b32_e32 v137, 0xffff0000, v67
	v_pk_fma_f32 v[8:9], v[8:9], v[128:129], v[130:131] op_sel_hi:[1,0,1]
	v_pk_fma_f32 v[10:11], v[10:11], v[128:129], v[132:133] op_sel_hi:[1,0,1]
	v_pk_fma_f32 v[12:13], v[12:13], v[128:129], v[134:135] op_sel_hi:[1,0,1]
	v_pk_fma_f32 v[14:15], v[14:15], v[128:129], v[136:137] op_sel_hi:[1,0,1]
	v_cvt_pk_bf16_f32 v124, v8, v9
	v_cvt_pk_bf16_f32 v125, v10, v11
	v_cvt_pk_bf16_f32 v126, v12, v13
	v_cvt_pk_bf16_f32 v127, v14, v15
	v_mul_f32_e32 v128, 0x3fb8aa3b, v114
	v_exp_f32_e32 v128, v128
	global_store_dwordx4 v0, v[124:127], s[98:99]
	s_add_u32 s98, s98, 0x8100
	s_addc_u32 s99, s99, 0
	v_lshlrev_b32_e32 v130, 16, v68
	v_and_b32_e32 v131, 0xffff0000, v68
	v_lshlrev_b32_e32 v132, 16, v69
	v_and_b32_e32 v133, 0xffff0000, v69
	v_lshlrev_b32_e32 v134, 16, v70
	v_and_b32_e32 v135, 0xffff0000, v70
	v_lshlrev_b32_e32 v136, 16, v71
	v_and_b32_e32 v137, 0xffff0000, v71
	v_pk_fma_f32 v[8:9], v[8:9], v[128:129], v[130:131] op_sel_hi:[1,0,1]
	v_pk_fma_f32 v[10:11], v[10:11], v[128:129], v[132:133] op_sel_hi:[1,0,1]
	v_pk_fma_f32 v[12:13], v[12:13], v[128:129], v[134:135] op_sel_hi:[1,0,1]
	v_pk_fma_f32 v[14:15], v[14:15], v[128:129], v[136:137] op_sel_hi:[1,0,1]
	v_cvt_pk_bf16_f32 v124, v8, v9
	v_cvt_pk_bf16_f32 v125, v10, v11
	v_cvt_pk_bf16_f32 v126, v12, v13
	v_cvt_pk_bf16_f32 v127, v14, v15
	v_mul_f32_e32 v128, 0x3fb8aa3b, v115
	v_exp_f32_e32 v128, v128
	global_store_dwordx4 v0, v[124:127], s[98:99]
	s_add_u32 s98, s98, 0x8100
	s_addc_u32 s99, s99, 0
	v_lshlrev_b32_e32 v130, 16, v72
	v_and_b32_e32 v131, 0xffff0000, v72
	v_lshlrev_b32_e32 v132, 16, v73
	v_and_b32_e32 v133, 0xffff0000, v73
	v_lshlrev_b32_e32 v134, 16, v74
	v_and_b32_e32 v135, 0xffff0000, v74
	v_lshlrev_b32_e32 v136, 16, v75
	v_and_b32_e32 v137, 0xffff0000, v75
	v_pk_fma_f32 v[8:9], v[8:9], v[128:129], v[130:131] op_sel_hi:[1,0,1]
	v_pk_fma_f32 v[10:11], v[10:11], v[128:129], v[132:133] op_sel_hi:[1,0,1]
	v_pk_fma_f32 v[12:13], v[12:13], v[128:129], v[134:135] op_sel_hi:[1,0,1]
	v_pk_fma_f32 v[14:15], v[14:15], v[128:129], v[136:137] op_sel_hi:[1,0,1]
	global_load_dwordx4 v[44:47], v0, s[100:101]
	s_add_u32 s100, s100, 0x8100
	s_addc_u32 s101, s101, 0
	global_load_dwordx4 v[48:51], v0, s[100:101]
	s_add_u32 s100, s100, 0x8100
	s_addc_u32 s101, s101, 0
	global_load_dwordx4 v[52:55], v0, s[100:101]
	s_add_u32 s100, s100, 0x8100
	s_addc_u32 s101, s101, 0
	global_load_dwordx4 v[56:59], v0, s[100:101]
	s_add_u32 s100, s100, 0x8100
	s_addc_u32 s101, s101, 0
	global_load_dwordx4 v[60:63], v0, s[100:101]
	s_add_u32 s100, s100, 0x8100
	s_addc_u32 s101, s101, 0
	global_load_dwordx4 v[64:67], v0, s[100:101]
	s_add_u32 s100, s100, 0x8100
	s_addc_u32 s101, s101, 0
	global_load_dwordx4 v[68:71], v0, s[100:101]
	s_add_u32 s100, s100, 0x8100
	s_addc_u32 s101, s101, 0
	global_load_dwordx4 v[72:75], v0, s[100:101]
	s_add_u32 s100, s100, 0x8100
	s_addc_u32 s101, s101, 0
	global_load_dword v108, v2, s[58:59] offset:64
	global_load_dword v109, v2, s[58:59] offset:68
	global_load_dword v110, v2, s[58:59] offset:72
	global_load_dword v111, v2, s[58:59] offset:76
	global_load_dword v112, v2, s[58:59] offset:80
	global_load_dword v113, v2, s[58:59] offset:84
	global_load_dword v114, v2, s[58:59] offset:88
	global_load_dword v115, v2, s[58:59] offset:92
	s_waitcnt vmcnt(24)
	v_cvt_pk_bf16_f32 v124, v8, v9
	v_cvt_pk_bf16_f32 v125, v10, v11
	v_cvt_pk_bf16_f32 v126, v12, v13
	v_cvt_pk_bf16_f32 v127, v14, v15
	v_mul_f32_e32 v128, 0x3fb8aa3b, v116
	v_exp_f32_e32 v128, v128
	global_store_dwordx4 v0, v[124:127], s[98:99]
	s_add_u32 s98, s98, 0x8100
	s_addc_u32 s99, s99, 0
	v_lshlrev_b32_e32 v130, 16, v76
	v_and_b32_e32 v131, 0xffff0000, v76
	v_lshlrev_b32_e32 v132, 16, v77
	v_and_b32_e32 v133, 0xffff0000, v77
	v_lshlrev_b32_e32 v134, 16, v78
	v_and_b32_e32 v135, 0xffff0000, v78
	v_lshlrev_b32_e32 v136, 16, v79
	v_and_b32_e32 v137, 0xffff0000, v79
	v_pk_fma_f32 v[8:9], v[8:9], v[128:129], v[130:131] op_sel_hi:[1,0,1]
	v_pk_fma_f32 v[10:11], v[10:11], v[128:129], v[132:133] op_sel_hi:[1,0,1]
	v_pk_fma_f32 v[12:13], v[12:13], v[128:129], v[134:135] op_sel_hi:[1,0,1]
	v_pk_fma_f32 v[14:15], v[14:15], v[128:129], v[136:137] op_sel_hi:[1,0,1]
	v_cvt_pk_bf16_f32 v124, v8, v9
	v_cvt_pk_bf16_f32 v125, v10, v11
	v_cvt_pk_bf16_f32 v126, v12, v13
	v_cvt_pk_bf16_f32 v127, v14, v15
	v_mul_f32_e32 v128, 0x3fb8aa3b, v117
	v_exp_f32_e32 v128, v128
	global_store_dwordx4 v0, v[124:127], s[98:99]
	s_add_u32 s98, s98, 0x8100
	s_addc_u32 s99, s99, 0
	v_lshlrev_b32_e32 v130, 16, v80
	v_and_b32_e32 v131, 0xffff0000, v80
	v_lshlrev_b32_e32 v132, 16, v81
	v_and_b32_e32 v133, 0xffff0000, v81
	v_lshlrev_b32_e32 v134, 16, v82
	v_and_b32_e32 v135, 0xffff0000, v82
	v_lshlrev_b32_e32 v136, 16, v83
	v_and_b32_e32 v137, 0xffff0000, v83
	v_pk_fma_f32 v[8:9], v[8:9], v[128:129], v[130:131] op_sel_hi:[1,0,1]
	v_pk_fma_f32 v[10:11], v[10:11], v[128:129], v[132:133] op_sel_hi:[1,0,1]
	v_pk_fma_f32 v[12:13], v[12:13], v[128:129], v[134:135] op_sel_hi:[1,0,1]
	v_pk_fma_f32 v[14:15], v[14:15], v[128:129], v[136:137] op_sel_hi:[1,0,1]
	v_cvt_pk_bf16_f32 v124, v8, v9
	v_cvt_pk_bf16_f32 v125, v10, v11
	v_cvt_pk_bf16_f32 v126, v12, v13
	v_cvt_pk_bf16_f32 v127, v14, v15
	v_mul_f32_e32 v128, 0x3fb8aa3b, v118
	v_exp_f32_e32 v128, v128
	global_store_dwordx4 v0, v[124:127], s[98:99]
	s_add_u32 s98, s98, 0x8100
	s_addc_u32 s99, s99, 0
	v_lshlrev_b32_e32 v130, 16, v84
	v_and_b32_e32 v131, 0xffff0000, v84
	v_lshlrev_b32_e32 v132, 16, v85
	v_and_b32_e32 v133, 0xffff0000, v85
	v_lshlrev_b32_e32 v134, 16, v86
	v_and_b32_e32 v135, 0xffff0000, v86
	v_lshlrev_b32_e32 v136, 16, v87
	v_and_b32_e32 v137, 0xffff0000, v87
	v_pk_fma_f32 v[8:9], v[8:9], v[128:129], v[130:131] op_sel_hi:[1,0,1]
	v_pk_fma_f32 v[10:11], v[10:11], v[128:129], v[132:133] op_sel_hi:[1,0,1]
	v_pk_fma_f32 v[12:13], v[12:13], v[128:129], v[134:135] op_sel_hi:[1,0,1]
	v_pk_fma_f32 v[14:15], v[14:15], v[128:129], v[136:137] op_sel_hi:[1,0,1]
	v_cvt_pk_bf16_f32 v124, v8, v9
	v_cvt_pk_bf16_f32 v125, v10, v11
	v_cvt_pk_bf16_f32 v126, v12, v13
	v_cvt_pk_bf16_f32 v127, v14, v15
	v_mul_f32_e32 v128, 0x3fb8aa3b, v119
	v_exp_f32_e32 v128, v128
	global_store_dwordx4 v0, v[124:127], s[98:99]
	s_add_u32 s98, s98, 0x8100
	s_addc_u32 s99, s99, 0
	v_lshlrev_b32_e32 v130, 16, v88
	v_and_b32_e32 v131, 0xffff0000, v88
	v_lshlrev_b32_e32 v132, 16, v89
	v_and_b32_e32 v133, 0xffff0000, v89
	v_lshlrev_b32_e32 v134, 16, v90
	v_and_b32_e32 v135, 0xffff0000, v90
	v_lshlrev_b32_e32 v136, 16, v91
	v_and_b32_e32 v137, 0xffff0000, v91
	v_pk_fma_f32 v[8:9], v[8:9], v[128:129], v[130:131] op_sel_hi:[1,0,1]
	v_pk_fma_f32 v[10:11], v[10:11], v[128:129], v[132:133] op_sel_hi:[1,0,1]
	v_pk_fma_f32 v[12:13], v[12:13], v[128:129], v[134:135] op_sel_hi:[1,0,1]
	v_pk_fma_f32 v[14:15], v[14:15], v[128:129], v[136:137] op_sel_hi:[1,0,1]
	v_cvt_pk_bf16_f32 v124, v8, v9
	v_cvt_pk_bf16_f32 v125, v10, v11
	v_cvt_pk_bf16_f32 v126, v12, v13
	v_cvt_pk_bf16_f32 v127, v14, v15
	v_mul_f32_e32 v128, 0x3fb8aa3b, v120
	v_exp_f32_e32 v128, v128
	global_store_dwordx4 v0, v[124:127], s[98:99]
	s_add_u32 s98, s98, 0x8100
	s_addc_u32 s99, s99, 0
	v_lshlrev_b32_e32 v130, 16, v92
	v_and_b32_e32 v131, 0xffff0000, v92
	v_lshlrev_b32_e32 v132, 16, v93
	v_and_b32_e32 v133, 0xffff0000, v93
	v_lshlrev_b32_e32 v134, 16, v94
	v_and_b32_e32 v135, 0xffff0000, v94
	v_lshlrev_b32_e32 v136, 16, v95
	v_and_b32_e32 v137, 0xffff0000, v95
	v_pk_fma_f32 v[8:9], v[8:9], v[128:129], v[130:131] op_sel_hi:[1,0,1]
	v_pk_fma_f32 v[10:11], v[10:11], v[128:129], v[132:133] op_sel_hi:[1,0,1]
	v_pk_fma_f32 v[12:13], v[12:13], v[128:129], v[134:135] op_sel_hi:[1,0,1]
	v_pk_fma_f32 v[14:15], v[14:15], v[128:129], v[136:137] op_sel_hi:[1,0,1]
	v_cvt_pk_bf16_f32 v124, v8, v9
	v_cvt_pk_bf16_f32 v125, v10, v11
	v_cvt_pk_bf16_f32 v126, v12, v13
	v_cvt_pk_bf16_f32 v127, v14, v15
	v_mul_f32_e32 v128, 0x3fb8aa3b, v121
	v_exp_f32_e32 v128, v128
	global_store_dwordx4 v0, v[124:127], s[98:99]
	s_add_u32 s98, s98, 0x8100
	s_addc_u32 s99, s99, 0
	v_lshlrev_b32_e32 v130, 16, v96
	v_and_b32_e32 v131, 0xffff0000, v96
	v_lshlrev_b32_e32 v132, 16, v97
	v_and_b32_e32 v133, 0xffff0000, v97
	v_lshlrev_b32_e32 v134, 16, v98
	v_and_b32_e32 v135, 0xffff0000, v98
	v_lshlrev_b32_e32 v136, 16, v99
	v_and_b32_e32 v137, 0xffff0000, v99
	v_pk_fma_f32 v[8:9], v[8:9], v[128:129], v[130:131] op_sel_hi:[1,0,1]
	v_pk_fma_f32 v[10:11], v[10:11], v[128:129], v[132:133] op_sel_hi:[1,0,1]
	v_pk_fma_f32 v[12:13], v[12:13], v[128:129], v[134:135] op_sel_hi:[1,0,1]
	v_pk_fma_f32 v[14:15], v[14:15], v[128:129], v[136:137] op_sel_hi:[1,0,1]
	v_cvt_pk_bf16_f32 v124, v8, v9
	v_cvt_pk_bf16_f32 v125, v10, v11
	v_cvt_pk_bf16_f32 v126, v12, v13
	v_cvt_pk_bf16_f32 v127, v14, v15
	v_mul_f32_e32 v128, 0x3fb8aa3b, v122
	v_exp_f32_e32 v128, v128
	global_store_dwordx4 v0, v[124:127], s[98:99]
	s_add_u32 s98, s98, 0x8100
	s_addc_u32 s99, s99, 0
	v_lshlrev_b32_e32 v130, 16, v100
	v_and_b32_e32 v131, 0xffff0000, v100
	v_lshlrev_b32_e32 v132, 16, v101
	v_and_b32_e32 v133, 0xffff0000, v101
	v_lshlrev_b32_e32 v134, 16, v102
	v_and_b32_e32 v135, 0xffff0000, v102
	v_lshlrev_b32_e32 v136, 16, v103
	v_and_b32_e32 v137, 0xffff0000, v103
	v_pk_fma_f32 v[8:9], v[8:9], v[128:129], v[130:131] op_sel_hi:[1,0,1]
	v_pk_fma_f32 v[10:11], v[10:11], v[128:129], v[132:133] op_sel_hi:[1,0,1]
	v_pk_fma_f32 v[12:13], v[12:13], v[128:129], v[134:135] op_sel_hi:[1,0,1]
	v_pk_fma_f32 v[14:15], v[14:15], v[128:129], v[136:137] op_sel_hi:[1,0,1]
	v_cvt_pk_bf16_f32 v124, v8, v9
	v_cvt_pk_bf16_f32 v125, v10, v11
	v_cvt_pk_bf16_f32 v126, v12, v13
	v_cvt_pk_bf16_f32 v127, v14, v15
	v_mul_f32_e32 v128, 0x3fb8aa3b, v123
	v_exp_f32_e32 v128, v128
	global_store_dwordx4 v0, v[124:127], s[98:99]
	s_add_u32 s98, s98, 0x8100
	s_addc_u32 s99, s99, 0
	v_lshlrev_b32_e32 v130, 16, v104
	v_and_b32_e32 v131, 0xffff0000, v104
	v_lshlrev_b32_e32 v132, 16, v105
	v_and_b32_e32 v133, 0xffff0000, v105
	v_lshlrev_b32_e32 v134, 16, v106
	v_and_b32_e32 v135, 0xffff0000, v106
	v_lshlrev_b32_e32 v136, 16, v107
	v_and_b32_e32 v137, 0xffff0000, v107
	v_pk_fma_f32 v[8:9], v[8:9], v[128:129], v[130:131] op_sel_hi:[1,0,1]
	v_pk_fma_f32 v[10:11], v[10:11], v[128:129], v[132:133] op_sel_hi:[1,0,1]
	v_pk_fma_f32 v[12:13], v[12:13], v[128:129], v[134:135] op_sel_hi:[1,0,1]
	v_pk_fma_f32 v[14:15], v[14:15], v[128:129], v[136:137] op_sel_hi:[1,0,1]
	global_load_dwordx4 v[76:79], v0, s[100:101]
	s_add_u32 s100, s100, 0x8100
	s_addc_u32 s101, s101, 0
	global_load_dwordx4 v[80:83], v0, s[100:101]
	s_add_u32 s100, s100, 0x8100
	s_addc_u32 s101, s101, 0
	global_load_dwordx4 v[84:87], v0, s[100:101]
	s_add_u32 s100, s100, 0x8100
	s_addc_u32 s101, s101, 0
	global_load_dwordx4 v[88:91], v0, s[100:101]
	s_add_u32 s100, s100, 0x8100
	s_addc_u32 s101, s101, 0
	global_load_dwordx4 v[92:95], v0, s[100:101]
	s_add_u32 s100, s100, 0x8100
	s_addc_u32 s101, s101, 0
	global_load_dwordx4 v[96:99], v0, s[100:101]
	s_add_u32 s100, s100, 0x8100
	s_addc_u32 s101, s101, 0
	global_load_dwordx4 v[100:103], v0, s[100:101]
	s_add_u32 s100, s100, 0x8100
	s_addc_u32 s101, s101, 0
	global_load_dwordx4 v[104:107], v0, s[100:101]
	s_add_u32 s100, s100, 0x8100
	s_addc_u32 s101, s101, 0
	global_load_dword v116, v2, s[58:59] offset:96
	global_load_dword v117, v2, s[58:59] offset:100
	global_load_dword v118, v2, s[58:59] offset:104
	global_load_dword v119, v2, s[58:59] offset:108
	global_load_dword v120, v2, s[58:59] offset:112
	global_load_dword v121, v2, s[58:59] offset:116
	global_load_dword v122, v2, s[58:59] offset:120
	global_load_dword v123, v2, s[58:59] offset:124
	s_waitcnt vmcnt(24)
	v_cvt_pk_bf16_f32 v124, v8, v9
	v_cvt_pk_bf16_f32 v125, v10, v11
	v_cvt_pk_bf16_f32 v126, v12, v13
	v_cvt_pk_bf16_f32 v127, v14, v15
	v_mul_f32_e32 v128, 0x3fb8aa3b, v108
	v_exp_f32_e32 v128, v128
	global_store_dwordx4 v0, v[124:127], s[98:99]
	s_add_u32 s98, s98, 0x8100
	s_addc_u32 s99, s99, 0
	v_lshlrev_b32_e32 v130, 16, v44
	v_and_b32_e32 v131, 0xffff0000, v44
	v_lshlrev_b32_e32 v132, 16, v45
	v_and_b32_e32 v133, 0xffff0000, v45
	v_lshlrev_b32_e32 v134, 16, v46
	v_and_b32_e32 v135, 0xffff0000, v46
	v_lshlrev_b32_e32 v136, 16, v47
	v_and_b32_e32 v137, 0xffff0000, v47
	v_pk_fma_f32 v[8:9], v[8:9], v[128:129], v[130:131] op_sel_hi:[1,0,1]
	v_pk_fma_f32 v[10:11], v[10:11], v[128:129], v[132:133] op_sel_hi:[1,0,1]
	v_pk_fma_f32 v[12:13], v[12:13], v[128:129], v[134:135] op_sel_hi:[1,0,1]
	v_pk_fma_f32 v[14:15], v[14:15], v[128:129], v[136:137] op_sel_hi:[1,0,1]
	v_cvt_pk_bf16_f32 v124, v8, v9
	v_cvt_pk_bf16_f32 v125, v10, v11
	v_cvt_pk_bf16_f32 v126, v12, v13
	v_cvt_pk_bf16_f32 v127, v14, v15
	v_mul_f32_e32 v128, 0x3fb8aa3b, v109
	v_exp_f32_e32 v128, v128
	global_store_dwordx4 v0, v[124:127], s[98:99]
	s_add_u32 s98, s98, 0x8100
	s_addc_u32 s99, s99, 0
	v_lshlrev_b32_e32 v130, 16, v48
	v_and_b32_e32 v131, 0xffff0000, v48
	v_lshlrev_b32_e32 v132, 16, v49
	v_and_b32_e32 v133, 0xffff0000, v49
	v_lshlrev_b32_e32 v134, 16, v50
	v_and_b32_e32 v135, 0xffff0000, v50
	v_lshlrev_b32_e32 v136, 16, v51
	v_and_b32_e32 v137, 0xffff0000, v51
	v_pk_fma_f32 v[8:9], v[8:9], v[128:129], v[130:131] op_sel_hi:[1,0,1]
	v_pk_fma_f32 v[10:11], v[10:11], v[128:129], v[132:133] op_sel_hi:[1,0,1]
	v_pk_fma_f32 v[12:13], v[12:13], v[128:129], v[134:135] op_sel_hi:[1,0,1]
	v_pk_fma_f32 v[14:15], v[14:15], v[128:129], v[136:137] op_sel_hi:[1,0,1]
	v_cvt_pk_bf16_f32 v124, v8, v9
	v_cvt_pk_bf16_f32 v125, v10, v11
	v_cvt_pk_bf16_f32 v126, v12, v13
	v_cvt_pk_bf16_f32 v127, v14, v15
	v_mul_f32_e32 v128, 0x3fb8aa3b, v110
	v_exp_f32_e32 v128, v128
	global_store_dwordx4 v0, v[124:127], s[98:99]
	s_add_u32 s98, s98, 0x8100
	s_addc_u32 s99, s99, 0
	v_lshlrev_b32_e32 v130, 16, v52
	v_and_b32_e32 v131, 0xffff0000, v52
	v_lshlrev_b32_e32 v132, 16, v53
	v_and_b32_e32 v133, 0xffff0000, v53
	v_lshlrev_b32_e32 v134, 16, v54
	v_and_b32_e32 v135, 0xffff0000, v54
	v_lshlrev_b32_e32 v136, 16, v55
	v_and_b32_e32 v137, 0xffff0000, v55
	v_pk_fma_f32 v[8:9], v[8:9], v[128:129], v[130:131] op_sel_hi:[1,0,1]
	v_pk_fma_f32 v[10:11], v[10:11], v[128:129], v[132:133] op_sel_hi:[1,0,1]
	v_pk_fma_f32 v[12:13], v[12:13], v[128:129], v[134:135] op_sel_hi:[1,0,1]
	v_pk_fma_f32 v[14:15], v[14:15], v[128:129], v[136:137] op_sel_hi:[1,0,1]
	v_cvt_pk_bf16_f32 v124, v8, v9
	v_cvt_pk_bf16_f32 v125, v10, v11
	v_cvt_pk_bf16_f32 v126, v12, v13
	v_cvt_pk_bf16_f32 v127, v14, v15
	v_mul_f32_e32 v128, 0x3fb8aa3b, v111
	v_exp_f32_e32 v128, v128
	global_store_dwordx4 v0, v[124:127], s[98:99]
	s_add_u32 s98, s98, 0x8100
	s_addc_u32 s99, s99, 0
	v_lshlrev_b32_e32 v130, 16, v56
	v_and_b32_e32 v131, 0xffff0000, v56
	v_lshlrev_b32_e32 v132, 16, v57
	v_and_b32_e32 v133, 0xffff0000, v57
	v_lshlrev_b32_e32 v134, 16, v58
	v_and_b32_e32 v135, 0xffff0000, v58
	v_lshlrev_b32_e32 v136, 16, v59
	v_and_b32_e32 v137, 0xffff0000, v59
	v_pk_fma_f32 v[8:9], v[8:9], v[128:129], v[130:131] op_sel_hi:[1,0,1]
	v_pk_fma_f32 v[10:11], v[10:11], v[128:129], v[132:133] op_sel_hi:[1,0,1]
	v_pk_fma_f32 v[12:13], v[12:13], v[128:129], v[134:135] op_sel_hi:[1,0,1]
	v_pk_fma_f32 v[14:15], v[14:15], v[128:129], v[136:137] op_sel_hi:[1,0,1]
	v_cvt_pk_bf16_f32 v124, v8, v9
	v_cvt_pk_bf16_f32 v125, v10, v11
	v_cvt_pk_bf16_f32 v126, v12, v13
	v_cvt_pk_bf16_f32 v127, v14, v15
	v_mul_f32_e32 v128, 0x3fb8aa3b, v112
	v_exp_f32_e32 v128, v128
	global_store_dwordx4 v0, v[124:127], s[98:99]
	s_add_u32 s98, s98, 0x8100
	s_addc_u32 s99, s99, 0
	v_lshlrev_b32_e32 v130, 16, v60
	v_and_b32_e32 v131, 0xffff0000, v60
	v_lshlrev_b32_e32 v132, 16, v61
	v_and_b32_e32 v133, 0xffff0000, v61
	v_lshlrev_b32_e32 v134, 16, v62
	v_and_b32_e32 v135, 0xffff0000, v62
	v_lshlrev_b32_e32 v136, 16, v63
	v_and_b32_e32 v137, 0xffff0000, v63
	v_pk_fma_f32 v[8:9], v[8:9], v[128:129], v[130:131] op_sel_hi:[1,0,1]
	v_pk_fma_f32 v[10:11], v[10:11], v[128:129], v[132:133] op_sel_hi:[1,0,1]
	v_pk_fma_f32 v[12:13], v[12:13], v[128:129], v[134:135] op_sel_hi:[1,0,1]
	v_pk_fma_f32 v[14:15], v[14:15], v[128:129], v[136:137] op_sel_hi:[1,0,1]
	v_cvt_pk_bf16_f32 v124, v8, v9
	v_cvt_pk_bf16_f32 v125, v10, v11
	v_cvt_pk_bf16_f32 v126, v12, v13
	v_cvt_pk_bf16_f32 v127, v14, v15
	v_mul_f32_e32 v128, 0x3fb8aa3b, v113
	v_exp_f32_e32 v128, v128
	global_store_dwordx4 v0, v[124:127], s[98:99]
	s_add_u32 s98, s98, 0x8100
	s_addc_u32 s99, s99, 0
	v_lshlrev_b32_e32 v130, 16, v64
	v_and_b32_e32 v131, 0xffff0000, v64
	v_lshlrev_b32_e32 v132, 16, v65
	v_and_b32_e32 v133, 0xffff0000, v65
	v_lshlrev_b32_e32 v134, 16, v66
	v_and_b32_e32 v135, 0xffff0000, v66
	v_lshlrev_b32_e32 v136, 16, v67
	v_and_b32_e32 v137, 0xffff0000, v67
	v_pk_fma_f32 v[8:9], v[8:9], v[128:129], v[130:131] op_sel_hi:[1,0,1]
	v_pk_fma_f32 v[10:11], v[10:11], v[128:129], v[132:133] op_sel_hi:[1,0,1]
	v_pk_fma_f32 v[12:13], v[12:13], v[128:129], v[134:135] op_sel_hi:[1,0,1]
	v_pk_fma_f32 v[14:15], v[14:15], v[128:129], v[136:137] op_sel_hi:[1,0,1]
	v_cvt_pk_bf16_f32 v124, v8, v9
	v_cvt_pk_bf16_f32 v125, v10, v11
	v_cvt_pk_bf16_f32 v126, v12, v13
	v_cvt_pk_bf16_f32 v127, v14, v15
	v_mul_f32_e32 v128, 0x3fb8aa3b, v114
	v_exp_f32_e32 v128, v128
	global_store_dwordx4 v0, v[124:127], s[98:99]
	s_add_u32 s98, s98, 0x8100
	s_addc_u32 s99, s99, 0
	v_lshlrev_b32_e32 v130, 16, v68
	v_and_b32_e32 v131, 0xffff0000, v68
	v_lshlrev_b32_e32 v132, 16, v69
	v_and_b32_e32 v133, 0xffff0000, v69
	v_lshlrev_b32_e32 v134, 16, v70
	v_and_b32_e32 v135, 0xffff0000, v70
	v_lshlrev_b32_e32 v136, 16, v71
	v_and_b32_e32 v137, 0xffff0000, v71
	v_pk_fma_f32 v[8:9], v[8:9], v[128:129], v[130:131] op_sel_hi:[1,0,1]
	v_pk_fma_f32 v[10:11], v[10:11], v[128:129], v[132:133] op_sel_hi:[1,0,1]
	v_pk_fma_f32 v[12:13], v[12:13], v[128:129], v[134:135] op_sel_hi:[1,0,1]
	v_pk_fma_f32 v[14:15], v[14:15], v[128:129], v[136:137] op_sel_hi:[1,0,1]
	v_cvt_pk_bf16_f32 v124, v8, v9
	v_cvt_pk_bf16_f32 v125, v10, v11
	v_cvt_pk_bf16_f32 v126, v12, v13
	v_cvt_pk_bf16_f32 v127, v14, v15
	v_mul_f32_e32 v128, 0x3fb8aa3b, v115
	v_exp_f32_e32 v128, v128
	global_store_dwordx4 v0, v[124:127], s[98:99]
	s_add_u32 s98, s98, 0x8100
	s_addc_u32 s99, s99, 0
	v_lshlrev_b32_e32 v130, 16, v72
	v_and_b32_e32 v131, 0xffff0000, v72
	v_lshlrev_b32_e32 v132, 16, v73
	v_and_b32_e32 v133, 0xffff0000, v73
	v_lshlrev_b32_e32 v134, 16, v74
	v_and_b32_e32 v135, 0xffff0000, v74
	v_lshlrev_b32_e32 v136, 16, v75
	v_and_b32_e32 v137, 0xffff0000, v75
	v_pk_fma_f32 v[8:9], v[8:9], v[128:129], v[130:131] op_sel_hi:[1,0,1]
	v_pk_fma_f32 v[10:11], v[10:11], v[128:129], v[132:133] op_sel_hi:[1,0,1]
	v_pk_fma_f32 v[12:13], v[12:13], v[128:129], v[134:135] op_sel_hi:[1,0,1]
	v_pk_fma_f32 v[14:15], v[14:15], v[128:129], v[136:137] op_sel_hi:[1,0,1]
	global_load_dwordx4 v[44:47], v0, s[100:101]
	s_add_u32 s100, s100, 0x8100
	s_addc_u32 s101, s101, 0
	global_load_dwordx4 v[48:51], v0, s[100:101]
	s_add_u32 s100, s100, 0x8100
	s_addc_u32 s101, s101, 0
	global_load_dwordx4 v[52:55], v0, s[100:101]
	s_add_u32 s100, s100, 0x8100
	s_addc_u32 s101, s101, 0
	global_load_dwordx4 v[56:59], v0, s[100:101]
	s_add_u32 s100, s100, 0x8100
	s_addc_u32 s101, s101, 0
	global_load_dwordx4 v[60:63], v0, s[100:101]
	s_add_u32 s100, s100, 0x8100
	s_addc_u32 s101, s101, 0
	global_load_dwordx4 v[64:67], v0, s[100:101]
	s_add_u32 s100, s100, 0x8100
	s_addc_u32 s101, s101, 0
	global_load_dwordx4 v[68:71], v0, s[100:101]
	s_add_u32 s100, s100, 0x8100
	s_addc_u32 s101, s101, 0
	global_load_dwordx4 v[72:75], v0, s[100:101]
	s_add_u32 s100, s100, 0x8100
	s_addc_u32 s101, s101, 0
	global_load_dword v108, v2, s[58:59] offset:128
	global_load_dword v109, v2, s[58:59] offset:132
	global_load_dword v110, v2, s[58:59] offset:136
	global_load_dword v111, v2, s[58:59] offset:140
	global_load_dword v112, v2, s[58:59] offset:144
	global_load_dword v113, v2, s[58:59] offset:148
	global_load_dword v114, v2, s[58:59] offset:152
	global_load_dword v115, v2, s[58:59] offset:156
	s_waitcnt vmcnt(24)
	v_cvt_pk_bf16_f32 v124, v8, v9
	v_cvt_pk_bf16_f32 v125, v10, v11
	v_cvt_pk_bf16_f32 v126, v12, v13
	v_cvt_pk_bf16_f32 v127, v14, v15
	v_mul_f32_e32 v128, 0x3fb8aa3b, v116
	v_exp_f32_e32 v128, v128
	global_store_dwordx4 v0, v[124:127], s[98:99]
	s_add_u32 s98, s98, 0x8100
	s_addc_u32 s99, s99, 0
	v_lshlrev_b32_e32 v130, 16, v76
	v_and_b32_e32 v131, 0xffff0000, v76
	v_lshlrev_b32_e32 v132, 16, v77
	v_and_b32_e32 v133, 0xffff0000, v77
	v_lshlrev_b32_e32 v134, 16, v78
	v_and_b32_e32 v135, 0xffff0000, v78
	v_lshlrev_b32_e32 v136, 16, v79
	v_and_b32_e32 v137, 0xffff0000, v79
	v_pk_fma_f32 v[8:9], v[8:9], v[128:129], v[130:131] op_sel_hi:[1,0,1]
	v_pk_fma_f32 v[10:11], v[10:11], v[128:129], v[132:133] op_sel_hi:[1,0,1]
	v_pk_fma_f32 v[12:13], v[12:13], v[128:129], v[134:135] op_sel_hi:[1,0,1]
	v_pk_fma_f32 v[14:15], v[14:15], v[128:129], v[136:137] op_sel_hi:[1,0,1]
	v_cvt_pk_bf16_f32 v124, v8, v9
	v_cvt_pk_bf16_f32 v125, v10, v11
	v_cvt_pk_bf16_f32 v126, v12, v13
	v_cvt_pk_bf16_f32 v127, v14, v15
	v_mul_f32_e32 v128, 0x3fb8aa3b, v117
	v_exp_f32_e32 v128, v128
	global_store_dwordx4 v0, v[124:127], s[98:99]
	s_add_u32 s98, s98, 0x8100
	s_addc_u32 s99, s99, 0
	v_lshlrev_b32_e32 v130, 16, v80
	v_and_b32_e32 v131, 0xffff0000, v80
	v_lshlrev_b32_e32 v132, 16, v81
	v_and_b32_e32 v133, 0xffff0000, v81
	v_lshlrev_b32_e32 v134, 16, v82
	v_and_b32_e32 v135, 0xffff0000, v82
	v_lshlrev_b32_e32 v136, 16, v83
	v_and_b32_e32 v137, 0xffff0000, v83
	v_pk_fma_f32 v[8:9], v[8:9], v[128:129], v[130:131] op_sel_hi:[1,0,1]
	v_pk_fma_f32 v[10:11], v[10:11], v[128:129], v[132:133] op_sel_hi:[1,0,1]
	v_pk_fma_f32 v[12:13], v[12:13], v[128:129], v[134:135] op_sel_hi:[1,0,1]
	v_pk_fma_f32 v[14:15], v[14:15], v[128:129], v[136:137] op_sel_hi:[1,0,1]
	v_cvt_pk_bf16_f32 v124, v8, v9
	v_cvt_pk_bf16_f32 v125, v10, v11
	v_cvt_pk_bf16_f32 v126, v12, v13
	v_cvt_pk_bf16_f32 v127, v14, v15
	v_mul_f32_e32 v128, 0x3fb8aa3b, v118
	v_exp_f32_e32 v128, v128
	global_store_dwordx4 v0, v[124:127], s[98:99]
	s_add_u32 s98, s98, 0x8100
	s_addc_u32 s99, s99, 0
	v_lshlrev_b32_e32 v130, 16, v84
	v_and_b32_e32 v131, 0xffff0000, v84
	v_lshlrev_b32_e32 v132, 16, v85
	v_and_b32_e32 v133, 0xffff0000, v85
	v_lshlrev_b32_e32 v134, 16, v86
	v_and_b32_e32 v135, 0xffff0000, v86
	v_lshlrev_b32_e32 v136, 16, v87
	v_and_b32_e32 v137, 0xffff0000, v87
	v_pk_fma_f32 v[8:9], v[8:9], v[128:129], v[130:131] op_sel_hi:[1,0,1]
	v_pk_fma_f32 v[10:11], v[10:11], v[128:129], v[132:133] op_sel_hi:[1,0,1]
	v_pk_fma_f32 v[12:13], v[12:13], v[128:129], v[134:135] op_sel_hi:[1,0,1]
	v_pk_fma_f32 v[14:15], v[14:15], v[128:129], v[136:137] op_sel_hi:[1,0,1]
	v_cvt_pk_bf16_f32 v124, v8, v9
	v_cvt_pk_bf16_f32 v125, v10, v11
	v_cvt_pk_bf16_f32 v126, v12, v13
	v_cvt_pk_bf16_f32 v127, v14, v15
	v_mul_f32_e32 v128, 0x3fb8aa3b, v119
	v_exp_f32_e32 v128, v128
	global_store_dwordx4 v0, v[124:127], s[98:99]
	s_add_u32 s98, s98, 0x8100
	s_addc_u32 s99, s99, 0
	v_lshlrev_b32_e32 v130, 16, v88
	v_and_b32_e32 v131, 0xffff0000, v88
	v_lshlrev_b32_e32 v132, 16, v89
	v_and_b32_e32 v133, 0xffff0000, v89
	v_lshlrev_b32_e32 v134, 16, v90
	v_and_b32_e32 v135, 0xffff0000, v90
	v_lshlrev_b32_e32 v136, 16, v91
	v_and_b32_e32 v137, 0xffff0000, v91
	v_pk_fma_f32 v[8:9], v[8:9], v[128:129], v[130:131] op_sel_hi:[1,0,1]
	v_pk_fma_f32 v[10:11], v[10:11], v[128:129], v[132:133] op_sel_hi:[1,0,1]
	v_pk_fma_f32 v[12:13], v[12:13], v[128:129], v[134:135] op_sel_hi:[1,0,1]
	v_pk_fma_f32 v[14:15], v[14:15], v[128:129], v[136:137] op_sel_hi:[1,0,1]
	v_cvt_pk_bf16_f32 v124, v8, v9
	v_cvt_pk_bf16_f32 v125, v10, v11
	v_cvt_pk_bf16_f32 v126, v12, v13
	v_cvt_pk_bf16_f32 v127, v14, v15
	v_mul_f32_e32 v128, 0x3fb8aa3b, v120
	v_exp_f32_e32 v128, v128
	global_store_dwordx4 v0, v[124:127], s[98:99]
	s_add_u32 s98, s98, 0x8100
	s_addc_u32 s99, s99, 0
	v_lshlrev_b32_e32 v130, 16, v92
	v_and_b32_e32 v131, 0xffff0000, v92
	v_lshlrev_b32_e32 v132, 16, v93
	v_and_b32_e32 v133, 0xffff0000, v93
	v_lshlrev_b32_e32 v134, 16, v94
	v_and_b32_e32 v135, 0xffff0000, v94
	v_lshlrev_b32_e32 v136, 16, v95
	v_and_b32_e32 v137, 0xffff0000, v95
	v_pk_fma_f32 v[8:9], v[8:9], v[128:129], v[130:131] op_sel_hi:[1,0,1]
	v_pk_fma_f32 v[10:11], v[10:11], v[128:129], v[132:133] op_sel_hi:[1,0,1]
	v_pk_fma_f32 v[12:13], v[12:13], v[128:129], v[134:135] op_sel_hi:[1,0,1]
	v_pk_fma_f32 v[14:15], v[14:15], v[128:129], v[136:137] op_sel_hi:[1,0,1]
	v_cvt_pk_bf16_f32 v124, v8, v9
	v_cvt_pk_bf16_f32 v125, v10, v11
	v_cvt_pk_bf16_f32 v126, v12, v13
	v_cvt_pk_bf16_f32 v127, v14, v15
	v_mul_f32_e32 v128, 0x3fb8aa3b, v121
	v_exp_f32_e32 v128, v128
	global_store_dwordx4 v0, v[124:127], s[98:99]
	s_add_u32 s98, s98, 0x8100
	s_addc_u32 s99, s99, 0
	v_lshlrev_b32_e32 v130, 16, v96
	v_and_b32_e32 v131, 0xffff0000, v96
	v_lshlrev_b32_e32 v132, 16, v97
	v_and_b32_e32 v133, 0xffff0000, v97
	v_lshlrev_b32_e32 v134, 16, v98
	v_and_b32_e32 v135, 0xffff0000, v98
	v_lshlrev_b32_e32 v136, 16, v99
	v_and_b32_e32 v137, 0xffff0000, v99
	v_pk_fma_f32 v[8:9], v[8:9], v[128:129], v[130:131] op_sel_hi:[1,0,1]
	v_pk_fma_f32 v[10:11], v[10:11], v[128:129], v[132:133] op_sel_hi:[1,0,1]
	v_pk_fma_f32 v[12:13], v[12:13], v[128:129], v[134:135] op_sel_hi:[1,0,1]
	v_pk_fma_f32 v[14:15], v[14:15], v[128:129], v[136:137] op_sel_hi:[1,0,1]
	v_cvt_pk_bf16_f32 v124, v8, v9
	v_cvt_pk_bf16_f32 v125, v10, v11
	v_cvt_pk_bf16_f32 v126, v12, v13
	v_cvt_pk_bf16_f32 v127, v14, v15
	v_mul_f32_e32 v128, 0x3fb8aa3b, v122
	v_exp_f32_e32 v128, v128
	global_store_dwordx4 v0, v[124:127], s[98:99]
	s_add_u32 s98, s98, 0x8100
	s_addc_u32 s99, s99, 0
	v_lshlrev_b32_e32 v130, 16, v100
	v_and_b32_e32 v131, 0xffff0000, v100
	v_lshlrev_b32_e32 v132, 16, v101
	v_and_b32_e32 v133, 0xffff0000, v101
	v_lshlrev_b32_e32 v134, 16, v102
	v_and_b32_e32 v135, 0xffff0000, v102
	v_lshlrev_b32_e32 v136, 16, v103
	v_and_b32_e32 v137, 0xffff0000, v103
	v_pk_fma_f32 v[8:9], v[8:9], v[128:129], v[130:131] op_sel_hi:[1,0,1]
	v_pk_fma_f32 v[10:11], v[10:11], v[128:129], v[132:133] op_sel_hi:[1,0,1]
	v_pk_fma_f32 v[12:13], v[12:13], v[128:129], v[134:135] op_sel_hi:[1,0,1]
	v_pk_fma_f32 v[14:15], v[14:15], v[128:129], v[136:137] op_sel_hi:[1,0,1]
	v_cvt_pk_bf16_f32 v124, v8, v9
	v_cvt_pk_bf16_f32 v125, v10, v11
	v_cvt_pk_bf16_f32 v126, v12, v13
	v_cvt_pk_bf16_f32 v127, v14, v15
	v_mul_f32_e32 v128, 0x3fb8aa3b, v123
	v_exp_f32_e32 v128, v128
	global_store_dwordx4 v0, v[124:127], s[98:99]
	s_add_u32 s98, s98, 0x8100
	s_addc_u32 s99, s99, 0
	v_lshlrev_b32_e32 v130, 16, v104
	v_and_b32_e32 v131, 0xffff0000, v104
	v_lshlrev_b32_e32 v132, 16, v105
	v_and_b32_e32 v133, 0xffff0000, v105
	v_lshlrev_b32_e32 v134, 16, v106
	v_and_b32_e32 v135, 0xffff0000, v106
	v_lshlrev_b32_e32 v136, 16, v107
	v_and_b32_e32 v137, 0xffff0000, v107
	v_pk_fma_f32 v[8:9], v[8:9], v[128:129], v[130:131] op_sel_hi:[1,0,1]
	v_pk_fma_f32 v[10:11], v[10:11], v[128:129], v[132:133] op_sel_hi:[1,0,1]
	v_pk_fma_f32 v[12:13], v[12:13], v[128:129], v[134:135] op_sel_hi:[1,0,1]
	v_pk_fma_f32 v[14:15], v[14:15], v[128:129], v[136:137] op_sel_hi:[1,0,1]
	global_load_dwordx4 v[76:79], v0, s[100:101]
	s_add_u32 s100, s100, 0x8100
	s_addc_u32 s101, s101, 0
	global_load_dwordx4 v[80:83], v0, s[100:101]
	s_add_u32 s100, s100, 0x8100
	s_addc_u32 s101, s101, 0
	global_load_dwordx4 v[84:87], v0, s[100:101]
	s_add_u32 s100, s100, 0x8100
	s_addc_u32 s101, s101, 0
	global_load_dwordx4 v[88:91], v0, s[100:101]
	s_add_u32 s100, s100, 0x8100
	s_addc_u32 s101, s101, 0
	global_load_dwordx4 v[92:95], v0, s[100:101]
	s_add_u32 s100, s100, 0x8100
	s_addc_u32 s101, s101, 0
	global_load_dwordx4 v[96:99], v0, s[100:101]
	s_add_u32 s100, s100, 0x8100
	s_addc_u32 s101, s101, 0
	global_load_dwordx4 v[100:103], v0, s[100:101]
	s_add_u32 s100, s100, 0x8100
	s_addc_u32 s101, s101, 0
	global_load_dwordx4 v[104:107], v0, s[100:101]
	s_add_u32 s100, s100, 0x8100
	s_addc_u32 s101, s101, 0
	global_load_dword v116, v2, s[58:59] offset:160
	global_load_dword v117, v2, s[58:59] offset:164
	global_load_dword v118, v2, s[58:59] offset:168
	global_load_dword v119, v2, s[58:59] offset:172
	global_load_dword v120, v2, s[58:59] offset:176
	global_load_dword v121, v2, s[58:59] offset:180
	global_load_dword v122, v2, s[58:59] offset:184
	global_load_dword v123, v2, s[58:59] offset:188
	s_waitcnt vmcnt(24)
	v_cvt_pk_bf16_f32 v124, v8, v9
	v_cvt_pk_bf16_f32 v125, v10, v11
	v_cvt_pk_bf16_f32 v126, v12, v13
	v_cvt_pk_bf16_f32 v127, v14, v15
	v_mul_f32_e32 v128, 0x3fb8aa3b, v108
	v_exp_f32_e32 v128, v128
	global_store_dwordx4 v0, v[124:127], s[98:99]
	s_add_u32 s98, s98, 0x8100
	s_addc_u32 s99, s99, 0
	v_lshlrev_b32_e32 v130, 16, v44
	v_and_b32_e32 v131, 0xffff0000, v44
	v_lshlrev_b32_e32 v132, 16, v45
	v_and_b32_e32 v133, 0xffff0000, v45
	v_lshlrev_b32_e32 v134, 16, v46
	v_and_b32_e32 v135, 0xffff0000, v46
	v_lshlrev_b32_e32 v136, 16, v47
	v_and_b32_e32 v137, 0xffff0000, v47
	v_pk_fma_f32 v[8:9], v[8:9], v[128:129], v[130:131] op_sel_hi:[1,0,1]
	v_pk_fma_f32 v[10:11], v[10:11], v[128:129], v[132:133] op_sel_hi:[1,0,1]
	v_pk_fma_f32 v[12:13], v[12:13], v[128:129], v[134:135] op_sel_hi:[1,0,1]
	v_pk_fma_f32 v[14:15], v[14:15], v[128:129], v[136:137] op_sel_hi:[1,0,1]
	v_cvt_pk_bf16_f32 v124, v8, v9
	v_cvt_pk_bf16_f32 v125, v10, v11
	v_cvt_pk_bf16_f32 v126, v12, v13
	v_cvt_pk_bf16_f32 v127, v14, v15
	v_mul_f32_e32 v128, 0x3fb8aa3b, v109
	v_exp_f32_e32 v128, v128
	global_store_dwordx4 v0, v[124:127], s[98:99]
	s_add_u32 s98, s98, 0x8100
	s_addc_u32 s99, s99, 0
	v_lshlrev_b32_e32 v130, 16, v48
	v_and_b32_e32 v131, 0xffff0000, v48
	v_lshlrev_b32_e32 v132, 16, v49
	v_and_b32_e32 v133, 0xffff0000, v49
	v_lshlrev_b32_e32 v134, 16, v50
	v_and_b32_e32 v135, 0xffff0000, v50
	v_lshlrev_b32_e32 v136, 16, v51
	v_and_b32_e32 v137, 0xffff0000, v51
	v_pk_fma_f32 v[8:9], v[8:9], v[128:129], v[130:131] op_sel_hi:[1,0,1]
	v_pk_fma_f32 v[10:11], v[10:11], v[128:129], v[132:133] op_sel_hi:[1,0,1]
	v_pk_fma_f32 v[12:13], v[12:13], v[128:129], v[134:135] op_sel_hi:[1,0,1]
	v_pk_fma_f32 v[14:15], v[14:15], v[128:129], v[136:137] op_sel_hi:[1,0,1]
	v_cvt_pk_bf16_f32 v124, v8, v9
	v_cvt_pk_bf16_f32 v125, v10, v11
	v_cvt_pk_bf16_f32 v126, v12, v13
	v_cvt_pk_bf16_f32 v127, v14, v15
	v_mul_f32_e32 v128, 0x3fb8aa3b, v110
	v_exp_f32_e32 v128, v128
	global_store_dwordx4 v0, v[124:127], s[98:99]
	s_add_u32 s98, s98, 0x8100
	s_addc_u32 s99, s99, 0
	v_lshlrev_b32_e32 v130, 16, v52
	v_and_b32_e32 v131, 0xffff0000, v52
	v_lshlrev_b32_e32 v132, 16, v53
	v_and_b32_e32 v133, 0xffff0000, v53
	v_lshlrev_b32_e32 v134, 16, v54
	v_and_b32_e32 v135, 0xffff0000, v54
	v_lshlrev_b32_e32 v136, 16, v55
	v_and_b32_e32 v137, 0xffff0000, v55
	v_pk_fma_f32 v[8:9], v[8:9], v[128:129], v[130:131] op_sel_hi:[1,0,1]
	v_pk_fma_f32 v[10:11], v[10:11], v[128:129], v[132:133] op_sel_hi:[1,0,1]
	v_pk_fma_f32 v[12:13], v[12:13], v[128:129], v[134:135] op_sel_hi:[1,0,1]
	v_pk_fma_f32 v[14:15], v[14:15], v[128:129], v[136:137] op_sel_hi:[1,0,1]
	v_cvt_pk_bf16_f32 v124, v8, v9
	v_cvt_pk_bf16_f32 v125, v10, v11
	v_cvt_pk_bf16_f32 v126, v12, v13
	v_cvt_pk_bf16_f32 v127, v14, v15
	v_mul_f32_e32 v128, 0x3fb8aa3b, v111
	v_exp_f32_e32 v128, v128
	global_store_dwordx4 v0, v[124:127], s[98:99]
	s_add_u32 s98, s98, 0x8100
	s_addc_u32 s99, s99, 0
	v_lshlrev_b32_e32 v130, 16, v56
	v_and_b32_e32 v131, 0xffff0000, v56
	v_lshlrev_b32_e32 v132, 16, v57
	v_and_b32_e32 v133, 0xffff0000, v57
	v_lshlrev_b32_e32 v134, 16, v58
	v_and_b32_e32 v135, 0xffff0000, v58
	v_lshlrev_b32_e32 v136, 16, v59
	v_and_b32_e32 v137, 0xffff0000, v59
	v_pk_fma_f32 v[8:9], v[8:9], v[128:129], v[130:131] op_sel_hi:[1,0,1]
	v_pk_fma_f32 v[10:11], v[10:11], v[128:129], v[132:133] op_sel_hi:[1,0,1]
	v_pk_fma_f32 v[12:13], v[12:13], v[128:129], v[134:135] op_sel_hi:[1,0,1]
	v_pk_fma_f32 v[14:15], v[14:15], v[128:129], v[136:137] op_sel_hi:[1,0,1]
	v_cvt_pk_bf16_f32 v124, v8, v9
	v_cvt_pk_bf16_f32 v125, v10, v11
	v_cvt_pk_bf16_f32 v126, v12, v13
	v_cvt_pk_bf16_f32 v127, v14, v15
	v_mul_f32_e32 v128, 0x3fb8aa3b, v112
	v_exp_f32_e32 v128, v128
	global_store_dwordx4 v0, v[124:127], s[98:99]
	s_add_u32 s98, s98, 0x8100
	s_addc_u32 s99, s99, 0
	v_lshlrev_b32_e32 v130, 16, v60
	v_and_b32_e32 v131, 0xffff0000, v60
	v_lshlrev_b32_e32 v132, 16, v61
	v_and_b32_e32 v133, 0xffff0000, v61
	v_lshlrev_b32_e32 v134, 16, v62
	v_and_b32_e32 v135, 0xffff0000, v62
	v_lshlrev_b32_e32 v136, 16, v63
	v_and_b32_e32 v137, 0xffff0000, v63
	v_pk_fma_f32 v[8:9], v[8:9], v[128:129], v[130:131] op_sel_hi:[1,0,1]
	v_pk_fma_f32 v[10:11], v[10:11], v[128:129], v[132:133] op_sel_hi:[1,0,1]
	v_pk_fma_f32 v[12:13], v[12:13], v[128:129], v[134:135] op_sel_hi:[1,0,1]
	v_pk_fma_f32 v[14:15], v[14:15], v[128:129], v[136:137] op_sel_hi:[1,0,1]
	v_cvt_pk_bf16_f32 v124, v8, v9
	v_cvt_pk_bf16_f32 v125, v10, v11
	v_cvt_pk_bf16_f32 v126, v12, v13
	v_cvt_pk_bf16_f32 v127, v14, v15
	v_mul_f32_e32 v128, 0x3fb8aa3b, v113
	v_exp_f32_e32 v128, v128
	global_store_dwordx4 v0, v[124:127], s[98:99]
	s_add_u32 s98, s98, 0x8100
	s_addc_u32 s99, s99, 0
	v_lshlrev_b32_e32 v130, 16, v64
	v_and_b32_e32 v131, 0xffff0000, v64
	v_lshlrev_b32_e32 v132, 16, v65
	v_and_b32_e32 v133, 0xffff0000, v65
	v_lshlrev_b32_e32 v134, 16, v66
	v_and_b32_e32 v135, 0xffff0000, v66
	v_lshlrev_b32_e32 v136, 16, v67
	v_and_b32_e32 v137, 0xffff0000, v67
	v_pk_fma_f32 v[8:9], v[8:9], v[128:129], v[130:131] op_sel_hi:[1,0,1]
	v_pk_fma_f32 v[10:11], v[10:11], v[128:129], v[132:133] op_sel_hi:[1,0,1]
	v_pk_fma_f32 v[12:13], v[12:13], v[128:129], v[134:135] op_sel_hi:[1,0,1]
	v_pk_fma_f32 v[14:15], v[14:15], v[128:129], v[136:137] op_sel_hi:[1,0,1]
	v_cvt_pk_bf16_f32 v124, v8, v9
	v_cvt_pk_bf16_f32 v125, v10, v11
	v_cvt_pk_bf16_f32 v126, v12, v13
	v_cvt_pk_bf16_f32 v127, v14, v15
	v_mul_f32_e32 v128, 0x3fb8aa3b, v114
	v_exp_f32_e32 v128, v128
	global_store_dwordx4 v0, v[124:127], s[98:99]
	s_add_u32 s98, s98, 0x8100
	s_addc_u32 s99, s99, 0
	v_lshlrev_b32_e32 v130, 16, v68
	v_and_b32_e32 v131, 0xffff0000, v68
	v_lshlrev_b32_e32 v132, 16, v69
	v_and_b32_e32 v133, 0xffff0000, v69
	v_lshlrev_b32_e32 v134, 16, v70
	v_and_b32_e32 v135, 0xffff0000, v70
	v_lshlrev_b32_e32 v136, 16, v71
	v_and_b32_e32 v137, 0xffff0000, v71
	v_pk_fma_f32 v[8:9], v[8:9], v[128:129], v[130:131] op_sel_hi:[1,0,1]
	v_pk_fma_f32 v[10:11], v[10:11], v[128:129], v[132:133] op_sel_hi:[1,0,1]
	v_pk_fma_f32 v[12:13], v[12:13], v[128:129], v[134:135] op_sel_hi:[1,0,1]
	v_pk_fma_f32 v[14:15], v[14:15], v[128:129], v[136:137] op_sel_hi:[1,0,1]
	v_cvt_pk_bf16_f32 v124, v8, v9
	v_cvt_pk_bf16_f32 v125, v10, v11
	v_cvt_pk_bf16_f32 v126, v12, v13
	v_cvt_pk_bf16_f32 v127, v14, v15
	v_mul_f32_e32 v128, 0x3fb8aa3b, v115
	v_exp_f32_e32 v128, v128
	global_store_dwordx4 v0, v[124:127], s[98:99]
	s_add_u32 s98, s98, 0x8100
	s_addc_u32 s99, s99, 0
	v_lshlrev_b32_e32 v130, 16, v72
	v_and_b32_e32 v131, 0xffff0000, v72
	v_lshlrev_b32_e32 v132, 16, v73
	v_and_b32_e32 v133, 0xffff0000, v73
	v_lshlrev_b32_e32 v134, 16, v74
	v_and_b32_e32 v135, 0xffff0000, v74
	v_lshlrev_b32_e32 v136, 16, v75
	v_and_b32_e32 v137, 0xffff0000, v75
	v_pk_fma_f32 v[8:9], v[8:9], v[128:129], v[130:131] op_sel_hi:[1,0,1]
	v_pk_fma_f32 v[10:11], v[10:11], v[128:129], v[132:133] op_sel_hi:[1,0,1]
	v_pk_fma_f32 v[12:13], v[12:13], v[128:129], v[134:135] op_sel_hi:[1,0,1]
	v_pk_fma_f32 v[14:15], v[14:15], v[128:129], v[136:137] op_sel_hi:[1,0,1]
	global_load_dwordx4 v[44:47], v0, s[100:101]
	s_add_u32 s100, s100, 0x8100
	s_addc_u32 s101, s101, 0
	global_load_dwordx4 v[48:51], v0, s[100:101]
	s_add_u32 s100, s100, 0x8100
	s_addc_u32 s101, s101, 0
	global_load_dwordx4 v[52:55], v0, s[100:101]
	s_add_u32 s100, s100, 0x8100
	s_addc_u32 s101, s101, 0
	global_load_dwordx4 v[56:59], v0, s[100:101]
	s_add_u32 s100, s100, 0x8100
	s_addc_u32 s101, s101, 0
	global_load_dwordx4 v[60:63], v0, s[100:101]
	s_add_u32 s100, s100, 0x8100
	s_addc_u32 s101, s101, 0
	global_load_dwordx4 v[64:67], v0, s[100:101]
	s_add_u32 s100, s100, 0x8100
	s_addc_u32 s101, s101, 0
	global_load_dwordx4 v[68:71], v0, s[100:101]
	s_add_u32 s100, s100, 0x8100
	s_addc_u32 s101, s101, 0
	global_load_dwordx4 v[72:75], v0, s[100:101]
	s_add_u32 s100, s100, 0x8100
	s_addc_u32 s101, s101, 0
	global_load_dword v108, v2, s[58:59] offset:192
	global_load_dword v109, v2, s[58:59] offset:196
	global_load_dword v110, v2, s[58:59] offset:200
	global_load_dword v111, v2, s[58:59] offset:204
	global_load_dword v112, v2, s[58:59] offset:208
	global_load_dword v113, v2, s[58:59] offset:212
	global_load_dword v114, v2, s[58:59] offset:216
	global_load_dword v115, v2, s[58:59] offset:220
	s_waitcnt vmcnt(24)
	v_cvt_pk_bf16_f32 v124, v8, v9
	v_cvt_pk_bf16_f32 v125, v10, v11
	v_cvt_pk_bf16_f32 v126, v12, v13
	v_cvt_pk_bf16_f32 v127, v14, v15
	v_mul_f32_e32 v128, 0x3fb8aa3b, v116
	v_exp_f32_e32 v128, v128
	global_store_dwordx4 v0, v[124:127], s[98:99]
	s_add_u32 s98, s98, 0x8100
	s_addc_u32 s99, s99, 0
	v_lshlrev_b32_e32 v130, 16, v76
	v_and_b32_e32 v131, 0xffff0000, v76
	v_lshlrev_b32_e32 v132, 16, v77
	v_and_b32_e32 v133, 0xffff0000, v77
	v_lshlrev_b32_e32 v134, 16, v78
	v_and_b32_e32 v135, 0xffff0000, v78
	v_lshlrev_b32_e32 v136, 16, v79
	v_and_b32_e32 v137, 0xffff0000, v79
	v_pk_fma_f32 v[8:9], v[8:9], v[128:129], v[130:131] op_sel_hi:[1,0,1]
	v_pk_fma_f32 v[10:11], v[10:11], v[128:129], v[132:133] op_sel_hi:[1,0,1]
	v_pk_fma_f32 v[12:13], v[12:13], v[128:129], v[134:135] op_sel_hi:[1,0,1]
	v_pk_fma_f32 v[14:15], v[14:15], v[128:129], v[136:137] op_sel_hi:[1,0,1]
	v_cvt_pk_bf16_f32 v124, v8, v9
	v_cvt_pk_bf16_f32 v125, v10, v11
	v_cvt_pk_bf16_f32 v126, v12, v13
	v_cvt_pk_bf16_f32 v127, v14, v15
	v_mul_f32_e32 v128, 0x3fb8aa3b, v117
	v_exp_f32_e32 v128, v128
	global_store_dwordx4 v0, v[124:127], s[98:99]
	s_add_u32 s98, s98, 0x8100
	s_addc_u32 s99, s99, 0
	v_lshlrev_b32_e32 v130, 16, v80
	v_and_b32_e32 v131, 0xffff0000, v80
	v_lshlrev_b32_e32 v132, 16, v81
	v_and_b32_e32 v133, 0xffff0000, v81
	v_lshlrev_b32_e32 v134, 16, v82
	v_and_b32_e32 v135, 0xffff0000, v82
	v_lshlrev_b32_e32 v136, 16, v83
	v_and_b32_e32 v137, 0xffff0000, v83
	v_pk_fma_f32 v[8:9], v[8:9], v[128:129], v[130:131] op_sel_hi:[1,0,1]
	v_pk_fma_f32 v[10:11], v[10:11], v[128:129], v[132:133] op_sel_hi:[1,0,1]
	v_pk_fma_f32 v[12:13], v[12:13], v[128:129], v[134:135] op_sel_hi:[1,0,1]
	v_pk_fma_f32 v[14:15], v[14:15], v[128:129], v[136:137] op_sel_hi:[1,0,1]
	v_cvt_pk_bf16_f32 v124, v8, v9
	v_cvt_pk_bf16_f32 v125, v10, v11
	v_cvt_pk_bf16_f32 v126, v12, v13
	v_cvt_pk_bf16_f32 v127, v14, v15
	v_mul_f32_e32 v128, 0x3fb8aa3b, v118
	v_exp_f32_e32 v128, v128
	global_store_dwordx4 v0, v[124:127], s[98:99]
	s_add_u32 s98, s98, 0x8100
	s_addc_u32 s99, s99, 0
	v_lshlrev_b32_e32 v130, 16, v84
	v_and_b32_e32 v131, 0xffff0000, v84
	v_lshlrev_b32_e32 v132, 16, v85
	v_and_b32_e32 v133, 0xffff0000, v85
	v_lshlrev_b32_e32 v134, 16, v86
	v_and_b32_e32 v135, 0xffff0000, v86
	v_lshlrev_b32_e32 v136, 16, v87
	v_and_b32_e32 v137, 0xffff0000, v87
	v_pk_fma_f32 v[8:9], v[8:9], v[128:129], v[130:131] op_sel_hi:[1,0,1]
	v_pk_fma_f32 v[10:11], v[10:11], v[128:129], v[132:133] op_sel_hi:[1,0,1]
	v_pk_fma_f32 v[12:13], v[12:13], v[128:129], v[134:135] op_sel_hi:[1,0,1]
	v_pk_fma_f32 v[14:15], v[14:15], v[128:129], v[136:137] op_sel_hi:[1,0,1]
	v_cvt_pk_bf16_f32 v124, v8, v9
	v_cvt_pk_bf16_f32 v125, v10, v11
	v_cvt_pk_bf16_f32 v126, v12, v13
	v_cvt_pk_bf16_f32 v127, v14, v15
	v_mul_f32_e32 v128, 0x3fb8aa3b, v119
	v_exp_f32_e32 v128, v128
	global_store_dwordx4 v0, v[124:127], s[98:99]
	s_add_u32 s98, s98, 0x8100
	s_addc_u32 s99, s99, 0
	v_lshlrev_b32_e32 v130, 16, v88
	v_and_b32_e32 v131, 0xffff0000, v88
	v_lshlrev_b32_e32 v132, 16, v89
	v_and_b32_e32 v133, 0xffff0000, v89
	v_lshlrev_b32_e32 v134, 16, v90
	v_and_b32_e32 v135, 0xffff0000, v90
	v_lshlrev_b32_e32 v136, 16, v91
	v_and_b32_e32 v137, 0xffff0000, v91
	v_pk_fma_f32 v[8:9], v[8:9], v[128:129], v[130:131] op_sel_hi:[1,0,1]
	v_pk_fma_f32 v[10:11], v[10:11], v[128:129], v[132:133] op_sel_hi:[1,0,1]
	v_pk_fma_f32 v[12:13], v[12:13], v[128:129], v[134:135] op_sel_hi:[1,0,1]
	v_pk_fma_f32 v[14:15], v[14:15], v[128:129], v[136:137] op_sel_hi:[1,0,1]
	v_cvt_pk_bf16_f32 v124, v8, v9
	v_cvt_pk_bf16_f32 v125, v10, v11
	v_cvt_pk_bf16_f32 v126, v12, v13
	v_cvt_pk_bf16_f32 v127, v14, v15
	v_mul_f32_e32 v128, 0x3fb8aa3b, v120
	v_exp_f32_e32 v128, v128
	global_store_dwordx4 v0, v[124:127], s[98:99]
	s_add_u32 s98, s98, 0x8100
	s_addc_u32 s99, s99, 0
	v_lshlrev_b32_e32 v130, 16, v92
	v_and_b32_e32 v131, 0xffff0000, v92
	v_lshlrev_b32_e32 v132, 16, v93
	v_and_b32_e32 v133, 0xffff0000, v93
	v_lshlrev_b32_e32 v134, 16, v94
	v_and_b32_e32 v135, 0xffff0000, v94
	v_lshlrev_b32_e32 v136, 16, v95
	v_and_b32_e32 v137, 0xffff0000, v95
	v_pk_fma_f32 v[8:9], v[8:9], v[128:129], v[130:131] op_sel_hi:[1,0,1]
	v_pk_fma_f32 v[10:11], v[10:11], v[128:129], v[132:133] op_sel_hi:[1,0,1]
	v_pk_fma_f32 v[12:13], v[12:13], v[128:129], v[134:135] op_sel_hi:[1,0,1]
	v_pk_fma_f32 v[14:15], v[14:15], v[128:129], v[136:137] op_sel_hi:[1,0,1]
	v_cvt_pk_bf16_f32 v124, v8, v9
	v_cvt_pk_bf16_f32 v125, v10, v11
	v_cvt_pk_bf16_f32 v126, v12, v13
	v_cvt_pk_bf16_f32 v127, v14, v15
	v_mul_f32_e32 v128, 0x3fb8aa3b, v121
	v_exp_f32_e32 v128, v128
	global_store_dwordx4 v0, v[124:127], s[98:99]
	s_add_u32 s98, s98, 0x8100
	s_addc_u32 s99, s99, 0
	v_lshlrev_b32_e32 v130, 16, v96
	v_and_b32_e32 v131, 0xffff0000, v96
	v_lshlrev_b32_e32 v132, 16, v97
	v_and_b32_e32 v133, 0xffff0000, v97
	v_lshlrev_b32_e32 v134, 16, v98
	v_and_b32_e32 v135, 0xffff0000, v98
	v_lshlrev_b32_e32 v136, 16, v99
	v_and_b32_e32 v137, 0xffff0000, v99
	v_pk_fma_f32 v[8:9], v[8:9], v[128:129], v[130:131] op_sel_hi:[1,0,1]
	v_pk_fma_f32 v[10:11], v[10:11], v[128:129], v[132:133] op_sel_hi:[1,0,1]
	v_pk_fma_f32 v[12:13], v[12:13], v[128:129], v[134:135] op_sel_hi:[1,0,1]
	v_pk_fma_f32 v[14:15], v[14:15], v[128:129], v[136:137] op_sel_hi:[1,0,1]
	v_cvt_pk_bf16_f32 v124, v8, v9
	v_cvt_pk_bf16_f32 v125, v10, v11
	v_cvt_pk_bf16_f32 v126, v12, v13
	v_cvt_pk_bf16_f32 v127, v14, v15
	v_mul_f32_e32 v128, 0x3fb8aa3b, v122
	v_exp_f32_e32 v128, v128
	global_store_dwordx4 v0, v[124:127], s[98:99]
	s_add_u32 s98, s98, 0x8100
	s_addc_u32 s99, s99, 0
	v_lshlrev_b32_e32 v130, 16, v100
	v_and_b32_e32 v131, 0xffff0000, v100
	v_lshlrev_b32_e32 v132, 16, v101
	v_and_b32_e32 v133, 0xffff0000, v101
	v_lshlrev_b32_e32 v134, 16, v102
	v_and_b32_e32 v135, 0xffff0000, v102
	v_lshlrev_b32_e32 v136, 16, v103
	v_and_b32_e32 v137, 0xffff0000, v103
	v_pk_fma_f32 v[8:9], v[8:9], v[128:129], v[130:131] op_sel_hi:[1,0,1]
	v_pk_fma_f32 v[10:11], v[10:11], v[128:129], v[132:133] op_sel_hi:[1,0,1]
	v_pk_fma_f32 v[12:13], v[12:13], v[128:129], v[134:135] op_sel_hi:[1,0,1]
	v_pk_fma_f32 v[14:15], v[14:15], v[128:129], v[136:137] op_sel_hi:[1,0,1]
	v_cvt_pk_bf16_f32 v124, v8, v9
	v_cvt_pk_bf16_f32 v125, v10, v11
	v_cvt_pk_bf16_f32 v126, v12, v13
	v_cvt_pk_bf16_f32 v127, v14, v15
	v_mul_f32_e32 v128, 0x3fb8aa3b, v123
	v_exp_f32_e32 v128, v128
	global_store_dwordx4 v0, v[124:127], s[98:99]
	s_add_u32 s98, s98, 0x8100
	s_addc_u32 s99, s99, 0
	v_lshlrev_b32_e32 v130, 16, v104
	v_and_b32_e32 v131, 0xffff0000, v104
	v_lshlrev_b32_e32 v132, 16, v105
	v_and_b32_e32 v133, 0xffff0000, v105
	v_lshlrev_b32_e32 v134, 16, v106
	v_and_b32_e32 v135, 0xffff0000, v106
	v_lshlrev_b32_e32 v136, 16, v107
	v_and_b32_e32 v137, 0xffff0000, v107
	v_pk_fma_f32 v[8:9], v[8:9], v[128:129], v[130:131] op_sel_hi:[1,0,1]
	v_pk_fma_f32 v[10:11], v[10:11], v[128:129], v[132:133] op_sel_hi:[1,0,1]
	v_pk_fma_f32 v[12:13], v[12:13], v[128:129], v[134:135] op_sel_hi:[1,0,1]
	v_pk_fma_f32 v[14:15], v[14:15], v[128:129], v[136:137] op_sel_hi:[1,0,1]
	global_load_dwordx4 v[76:79], v0, s[100:101]
	s_add_u32 s100, s100, 0x8100
	s_addc_u32 s101, s101, 0
	global_load_dwordx4 v[80:83], v0, s[100:101]
	s_add_u32 s100, s100, 0x8100
	s_addc_u32 s101, s101, 0
	global_load_dwordx4 v[84:87], v0, s[100:101]
	s_add_u32 s100, s100, 0x8100
	s_addc_u32 s101, s101, 0
	global_load_dwordx4 v[88:91], v0, s[100:101]
	s_add_u32 s100, s100, 0x8100
	s_addc_u32 s101, s101, 0
	global_load_dwordx4 v[92:95], v0, s[100:101]
	s_add_u32 s100, s100, 0x8100
	s_addc_u32 s101, s101, 0
	global_load_dwordx4 v[96:99], v0, s[100:101]
	s_add_u32 s100, s100, 0x8100
	s_addc_u32 s101, s101, 0
	global_load_dwordx4 v[100:103], v0, s[100:101]
	s_add_u32 s100, s100, 0x8100
	s_addc_u32 s101, s101, 0
	global_load_dwordx4 v[104:107], v0, s[100:101]
	s_add_u32 s100, s100, 0x8100
	s_addc_u32 s101, s101, 0
	global_load_dword v116, v2, s[58:59] offset:224
	global_load_dword v117, v2, s[58:59] offset:228
	global_load_dword v118, v2, s[58:59] offset:232
	global_load_dword v119, v2, s[58:59] offset:236
	global_load_dword v120, v2, s[58:59] offset:240
	global_load_dword v121, v2, s[58:59] offset:244
	global_load_dword v122, v2, s[58:59] offset:248
	global_load_dword v123, v2, s[58:59] offset:252
	s_waitcnt vmcnt(24)
	v_cvt_pk_bf16_f32 v124, v8, v9
	v_cvt_pk_bf16_f32 v125, v10, v11
	v_cvt_pk_bf16_f32 v126, v12, v13
	v_cvt_pk_bf16_f32 v127, v14, v15
	v_mul_f32_e32 v128, 0x3fb8aa3b, v108
	v_exp_f32_e32 v128, v128
	global_store_dwordx4 v0, v[124:127], s[98:99]
	s_add_u32 s98, s98, 0x8100
	s_addc_u32 s99, s99, 0
	v_lshlrev_b32_e32 v130, 16, v44
	v_and_b32_e32 v131, 0xffff0000, v44
	v_lshlrev_b32_e32 v132, 16, v45
	v_and_b32_e32 v133, 0xffff0000, v45
	v_lshlrev_b32_e32 v134, 16, v46
	v_and_b32_e32 v135, 0xffff0000, v46
	v_lshlrev_b32_e32 v136, 16, v47
	v_and_b32_e32 v137, 0xffff0000, v47
	v_pk_fma_f32 v[8:9], v[8:9], v[128:129], v[130:131] op_sel_hi:[1,0,1]
	v_pk_fma_f32 v[10:11], v[10:11], v[128:129], v[132:133] op_sel_hi:[1,0,1]
	v_pk_fma_f32 v[12:13], v[12:13], v[128:129], v[134:135] op_sel_hi:[1,0,1]
	v_pk_fma_f32 v[14:15], v[14:15], v[128:129], v[136:137] op_sel_hi:[1,0,1]
	v_cvt_pk_bf16_f32 v124, v8, v9
	v_cvt_pk_bf16_f32 v125, v10, v11
	v_cvt_pk_bf16_f32 v126, v12, v13
	v_cvt_pk_bf16_f32 v127, v14, v15
	v_mul_f32_e32 v128, 0x3fb8aa3b, v109
	v_exp_f32_e32 v128, v128
	global_store_dwordx4 v0, v[124:127], s[98:99]
	s_add_u32 s98, s98, 0x8100
	s_addc_u32 s99, s99, 0
	v_lshlrev_b32_e32 v130, 16, v48
	v_and_b32_e32 v131, 0xffff0000, v48
	v_lshlrev_b32_e32 v132, 16, v49
	v_and_b32_e32 v133, 0xffff0000, v49
	v_lshlrev_b32_e32 v134, 16, v50
	v_and_b32_e32 v135, 0xffff0000, v50
	v_lshlrev_b32_e32 v136, 16, v51
	v_and_b32_e32 v137, 0xffff0000, v51
	v_pk_fma_f32 v[8:9], v[8:9], v[128:129], v[130:131] op_sel_hi:[1,0,1]
	v_pk_fma_f32 v[10:11], v[10:11], v[128:129], v[132:133] op_sel_hi:[1,0,1]
	v_pk_fma_f32 v[12:13], v[12:13], v[128:129], v[134:135] op_sel_hi:[1,0,1]
	v_pk_fma_f32 v[14:15], v[14:15], v[128:129], v[136:137] op_sel_hi:[1,0,1]
	v_cvt_pk_bf16_f32 v124, v8, v9
	v_cvt_pk_bf16_f32 v125, v10, v11
	v_cvt_pk_bf16_f32 v126, v12, v13
	v_cvt_pk_bf16_f32 v127, v14, v15
	v_mul_f32_e32 v128, 0x3fb8aa3b, v110
	v_exp_f32_e32 v128, v128
	global_store_dwordx4 v0, v[124:127], s[98:99]
	s_add_u32 s98, s98, 0x8100
	s_addc_u32 s99, s99, 0
	v_lshlrev_b32_e32 v130, 16, v52
	v_and_b32_e32 v131, 0xffff0000, v52
	v_lshlrev_b32_e32 v132, 16, v53
	v_and_b32_e32 v133, 0xffff0000, v53
	v_lshlrev_b32_e32 v134, 16, v54
	v_and_b32_e32 v135, 0xffff0000, v54
	v_lshlrev_b32_e32 v136, 16, v55
	v_and_b32_e32 v137, 0xffff0000, v55
	v_pk_fma_f32 v[8:9], v[8:9], v[128:129], v[130:131] op_sel_hi:[1,0,1]
	v_pk_fma_f32 v[10:11], v[10:11], v[128:129], v[132:133] op_sel_hi:[1,0,1]
	v_pk_fma_f32 v[12:13], v[12:13], v[128:129], v[134:135] op_sel_hi:[1,0,1]
	v_pk_fma_f32 v[14:15], v[14:15], v[128:129], v[136:137] op_sel_hi:[1,0,1]
	v_cvt_pk_bf16_f32 v124, v8, v9
	v_cvt_pk_bf16_f32 v125, v10, v11
	v_cvt_pk_bf16_f32 v126, v12, v13
	v_cvt_pk_bf16_f32 v127, v14, v15
	v_mul_f32_e32 v128, 0x3fb8aa3b, v111
	v_exp_f32_e32 v128, v128
	global_store_dwordx4 v0, v[124:127], s[98:99]
	s_add_u32 s98, s98, 0x8100
	s_addc_u32 s99, s99, 0
	v_lshlrev_b32_e32 v130, 16, v56
	v_and_b32_e32 v131, 0xffff0000, v56
	v_lshlrev_b32_e32 v132, 16, v57
	v_and_b32_e32 v133, 0xffff0000, v57
	v_lshlrev_b32_e32 v134, 16, v58
	v_and_b32_e32 v135, 0xffff0000, v58
	v_lshlrev_b32_e32 v136, 16, v59
	v_and_b32_e32 v137, 0xffff0000, v59
	v_pk_fma_f32 v[8:9], v[8:9], v[128:129], v[130:131] op_sel_hi:[1,0,1]
	v_pk_fma_f32 v[10:11], v[10:11], v[128:129], v[132:133] op_sel_hi:[1,0,1]
	v_pk_fma_f32 v[12:13], v[12:13], v[128:129], v[134:135] op_sel_hi:[1,0,1]
	v_pk_fma_f32 v[14:15], v[14:15], v[128:129], v[136:137] op_sel_hi:[1,0,1]
	v_cvt_pk_bf16_f32 v124, v8, v9
	v_cvt_pk_bf16_f32 v125, v10, v11
	v_cvt_pk_bf16_f32 v126, v12, v13
	v_cvt_pk_bf16_f32 v127, v14, v15
	v_mul_f32_e32 v128, 0x3fb8aa3b, v112
	v_exp_f32_e32 v128, v128
	global_store_dwordx4 v0, v[124:127], s[98:99]
	s_add_u32 s98, s98, 0x8100
	s_addc_u32 s99, s99, 0
	v_lshlrev_b32_e32 v130, 16, v60
	v_and_b32_e32 v131, 0xffff0000, v60
	v_lshlrev_b32_e32 v132, 16, v61
	v_and_b32_e32 v133, 0xffff0000, v61
	v_lshlrev_b32_e32 v134, 16, v62
	v_and_b32_e32 v135, 0xffff0000, v62
	v_lshlrev_b32_e32 v136, 16, v63
	v_and_b32_e32 v137, 0xffff0000, v63
	v_pk_fma_f32 v[8:9], v[8:9], v[128:129], v[130:131] op_sel_hi:[1,0,1]
	v_pk_fma_f32 v[10:11], v[10:11], v[128:129], v[132:133] op_sel_hi:[1,0,1]
	v_pk_fma_f32 v[12:13], v[12:13], v[128:129], v[134:135] op_sel_hi:[1,0,1]
	v_pk_fma_f32 v[14:15], v[14:15], v[128:129], v[136:137] op_sel_hi:[1,0,1]
	v_cvt_pk_bf16_f32 v124, v8, v9
	v_cvt_pk_bf16_f32 v125, v10, v11
	v_cvt_pk_bf16_f32 v126, v12, v13
	v_cvt_pk_bf16_f32 v127, v14, v15
	v_mul_f32_e32 v128, 0x3fb8aa3b, v113
	v_exp_f32_e32 v128, v128
	global_store_dwordx4 v0, v[124:127], s[98:99]
	s_add_u32 s98, s98, 0x8100
	s_addc_u32 s99, s99, 0
	v_lshlrev_b32_e32 v130, 16, v64
	v_and_b32_e32 v131, 0xffff0000, v64
	v_lshlrev_b32_e32 v132, 16, v65
	v_and_b32_e32 v133, 0xffff0000, v65
	v_lshlrev_b32_e32 v134, 16, v66
	v_and_b32_e32 v135, 0xffff0000, v66
	v_lshlrev_b32_e32 v136, 16, v67
	v_and_b32_e32 v137, 0xffff0000, v67
	v_pk_fma_f32 v[8:9], v[8:9], v[128:129], v[130:131] op_sel_hi:[1,0,1]
	v_pk_fma_f32 v[10:11], v[10:11], v[128:129], v[132:133] op_sel_hi:[1,0,1]
	v_pk_fma_f32 v[12:13], v[12:13], v[128:129], v[134:135] op_sel_hi:[1,0,1]
	v_pk_fma_f32 v[14:15], v[14:15], v[128:129], v[136:137] op_sel_hi:[1,0,1]
	v_cvt_pk_bf16_f32 v124, v8, v9
	v_cvt_pk_bf16_f32 v125, v10, v11
	v_cvt_pk_bf16_f32 v126, v12, v13
	v_cvt_pk_bf16_f32 v127, v14, v15
	v_mul_f32_e32 v128, 0x3fb8aa3b, v114
	v_exp_f32_e32 v128, v128
	global_store_dwordx4 v0, v[124:127], s[98:99]
	s_add_u32 s98, s98, 0x8100
	s_addc_u32 s99, s99, 0
	v_lshlrev_b32_e32 v130, 16, v68
	v_and_b32_e32 v131, 0xffff0000, v68
	v_lshlrev_b32_e32 v132, 16, v69
	v_and_b32_e32 v133, 0xffff0000, v69
	v_lshlrev_b32_e32 v134, 16, v70
	v_and_b32_e32 v135, 0xffff0000, v70
	v_lshlrev_b32_e32 v136, 16, v71
	v_and_b32_e32 v137, 0xffff0000, v71
	v_pk_fma_f32 v[8:9], v[8:9], v[128:129], v[130:131] op_sel_hi:[1,0,1]
	v_pk_fma_f32 v[10:11], v[10:11], v[128:129], v[132:133] op_sel_hi:[1,0,1]
	v_pk_fma_f32 v[12:13], v[12:13], v[128:129], v[134:135] op_sel_hi:[1,0,1]
	v_pk_fma_f32 v[14:15], v[14:15], v[128:129], v[136:137] op_sel_hi:[1,0,1]
	v_cvt_pk_bf16_f32 v124, v8, v9
	v_cvt_pk_bf16_f32 v125, v10, v11
	v_cvt_pk_bf16_f32 v126, v12, v13
	v_cvt_pk_bf16_f32 v127, v14, v15
	v_mul_f32_e32 v128, 0x3fb8aa3b, v115
	v_exp_f32_e32 v128, v128
	global_store_dwordx4 v0, v[124:127], s[98:99]
	s_add_u32 s98, s98, 0x8100
	s_addc_u32 s99, s99, 0
	v_lshlrev_b32_e32 v130, 16, v72
	v_and_b32_e32 v131, 0xffff0000, v72
	v_lshlrev_b32_e32 v132, 16, v73
	v_and_b32_e32 v133, 0xffff0000, v73
	v_lshlrev_b32_e32 v134, 16, v74
	v_and_b32_e32 v135, 0xffff0000, v74
	v_lshlrev_b32_e32 v136, 16, v75
	v_and_b32_e32 v137, 0xffff0000, v75
	v_pk_fma_f32 v[8:9], v[8:9], v[128:129], v[130:131] op_sel_hi:[1,0,1]
	v_pk_fma_f32 v[10:11], v[10:11], v[128:129], v[132:133] op_sel_hi:[1,0,1]
	v_pk_fma_f32 v[12:13], v[12:13], v[128:129], v[134:135] op_sel_hi:[1,0,1]
	v_pk_fma_f32 v[14:15], v[14:15], v[128:129], v[136:137] op_sel_hi:[1,0,1]
	s_waitcnt vmcnt(8)
	v_cvt_pk_bf16_f32 v124, v8, v9
	v_cvt_pk_bf16_f32 v125, v10, v11
	v_cvt_pk_bf16_f32 v126, v12, v13
	v_cvt_pk_bf16_f32 v127, v14, v15
	v_mul_f32_e32 v128, 0x3fb8aa3b, v116
	v_exp_f32_e32 v128, v128
	global_store_dwordx4 v0, v[124:127], s[98:99]
	s_add_u32 s98, s98, 0x8100
	s_addc_u32 s99, s99, 0
	v_lshlrev_b32_e32 v130, 16, v76
	v_and_b32_e32 v131, 0xffff0000, v76
	v_lshlrev_b32_e32 v132, 16, v77
	v_and_b32_e32 v133, 0xffff0000, v77
	v_lshlrev_b32_e32 v134, 16, v78
	v_and_b32_e32 v135, 0xffff0000, v78
	v_lshlrev_b32_e32 v136, 16, v79
	v_and_b32_e32 v137, 0xffff0000, v79
	v_pk_fma_f32 v[8:9], v[8:9], v[128:129], v[130:131] op_sel_hi:[1,0,1]
	v_pk_fma_f32 v[10:11], v[10:11], v[128:129], v[132:133] op_sel_hi:[1,0,1]
	v_pk_fma_f32 v[12:13], v[12:13], v[128:129], v[134:135] op_sel_hi:[1,0,1]
	v_pk_fma_f32 v[14:15], v[14:15], v[128:129], v[136:137] op_sel_hi:[1,0,1]
	v_cvt_pk_bf16_f32 v124, v8, v9
	v_cvt_pk_bf16_f32 v125, v10, v11
	v_cvt_pk_bf16_f32 v126, v12, v13
	v_cvt_pk_bf16_f32 v127, v14, v15
	v_mul_f32_e32 v128, 0x3fb8aa3b, v117
	v_exp_f32_e32 v128, v128
	global_store_dwordx4 v0, v[124:127], s[98:99]
	s_add_u32 s98, s98, 0x8100
	s_addc_u32 s99, s99, 0
	v_lshlrev_b32_e32 v130, 16, v80
	v_and_b32_e32 v131, 0xffff0000, v80
	v_lshlrev_b32_e32 v132, 16, v81
	v_and_b32_e32 v133, 0xffff0000, v81
	v_lshlrev_b32_e32 v134, 16, v82
	v_and_b32_e32 v135, 0xffff0000, v82
	v_lshlrev_b32_e32 v136, 16, v83
	v_and_b32_e32 v137, 0xffff0000, v83
	v_pk_fma_f32 v[8:9], v[8:9], v[128:129], v[130:131] op_sel_hi:[1,0,1]
	v_pk_fma_f32 v[10:11], v[10:11], v[128:129], v[132:133] op_sel_hi:[1,0,1]
	v_pk_fma_f32 v[12:13], v[12:13], v[128:129], v[134:135] op_sel_hi:[1,0,1]
	v_pk_fma_f32 v[14:15], v[14:15], v[128:129], v[136:137] op_sel_hi:[1,0,1]
	v_cvt_pk_bf16_f32 v124, v8, v9
	v_cvt_pk_bf16_f32 v125, v10, v11
	v_cvt_pk_bf16_f32 v126, v12, v13
	v_cvt_pk_bf16_f32 v127, v14, v15
	v_mul_f32_e32 v128, 0x3fb8aa3b, v118
	v_exp_f32_e32 v128, v128
	global_store_dwordx4 v0, v[124:127], s[98:99]
	s_add_u32 s98, s98, 0x8100
	s_addc_u32 s99, s99, 0
	v_lshlrev_b32_e32 v130, 16, v84
	v_and_b32_e32 v131, 0xffff0000, v84
	v_lshlrev_b32_e32 v132, 16, v85
	v_and_b32_e32 v133, 0xffff0000, v85
	v_lshlrev_b32_e32 v134, 16, v86
	v_and_b32_e32 v135, 0xffff0000, v86
	v_lshlrev_b32_e32 v136, 16, v87
	v_and_b32_e32 v137, 0xffff0000, v87
	v_pk_fma_f32 v[8:9], v[8:9], v[128:129], v[130:131] op_sel_hi:[1,0,1]
	v_pk_fma_f32 v[10:11], v[10:11], v[128:129], v[132:133] op_sel_hi:[1,0,1]
	v_pk_fma_f32 v[12:13], v[12:13], v[128:129], v[134:135] op_sel_hi:[1,0,1]
	v_pk_fma_f32 v[14:15], v[14:15], v[128:129], v[136:137] op_sel_hi:[1,0,1]
	v_cvt_pk_bf16_f32 v124, v8, v9
	v_cvt_pk_bf16_f32 v125, v10, v11
	v_cvt_pk_bf16_f32 v126, v12, v13
	v_cvt_pk_bf16_f32 v127, v14, v15
	v_mul_f32_e32 v128, 0x3fb8aa3b, v119
	v_exp_f32_e32 v128, v128
	global_store_dwordx4 v0, v[124:127], s[98:99]
	s_add_u32 s98, s98, 0x8100
	s_addc_u32 s99, s99, 0
	v_lshlrev_b32_e32 v130, 16, v88
	v_and_b32_e32 v131, 0xffff0000, v88
	v_lshlrev_b32_e32 v132, 16, v89
	v_and_b32_e32 v133, 0xffff0000, v89
	v_lshlrev_b32_e32 v134, 16, v90
	v_and_b32_e32 v135, 0xffff0000, v90
	v_lshlrev_b32_e32 v136, 16, v91
	v_and_b32_e32 v137, 0xffff0000, v91
	v_pk_fma_f32 v[8:9], v[8:9], v[128:129], v[130:131] op_sel_hi:[1,0,1]
	v_pk_fma_f32 v[10:11], v[10:11], v[128:129], v[132:133] op_sel_hi:[1,0,1]
	v_pk_fma_f32 v[12:13], v[12:13], v[128:129], v[134:135] op_sel_hi:[1,0,1]
	v_pk_fma_f32 v[14:15], v[14:15], v[128:129], v[136:137] op_sel_hi:[1,0,1]
	v_cvt_pk_bf16_f32 v124, v8, v9
	v_cvt_pk_bf16_f32 v125, v10, v11
	v_cvt_pk_bf16_f32 v126, v12, v13
	v_cvt_pk_bf16_f32 v127, v14, v15
	v_mul_f32_e32 v128, 0x3fb8aa3b, v120
	v_exp_f32_e32 v128, v128
	global_store_dwordx4 v0, v[124:127], s[98:99]
	s_add_u32 s98, s98, 0x8100
	s_addc_u32 s99, s99, 0
	v_lshlrev_b32_e32 v130, 16, v92
	v_and_b32_e32 v131, 0xffff0000, v92
	v_lshlrev_b32_e32 v132, 16, v93
	v_and_b32_e32 v133, 0xffff0000, v93
	v_lshlrev_b32_e32 v134, 16, v94
	v_and_b32_e32 v135, 0xffff0000, v94
	v_lshlrev_b32_e32 v136, 16, v95
	v_and_b32_e32 v137, 0xffff0000, v95
	v_pk_fma_f32 v[8:9], v[8:9], v[128:129], v[130:131] op_sel_hi:[1,0,1]
	v_pk_fma_f32 v[10:11], v[10:11], v[128:129], v[132:133] op_sel_hi:[1,0,1]
	v_pk_fma_f32 v[12:13], v[12:13], v[128:129], v[134:135] op_sel_hi:[1,0,1]
	v_pk_fma_f32 v[14:15], v[14:15], v[128:129], v[136:137] op_sel_hi:[1,0,1]
	v_cvt_pk_bf16_f32 v124, v8, v9
	v_cvt_pk_bf16_f32 v125, v10, v11
	v_cvt_pk_bf16_f32 v126, v12, v13
	v_cvt_pk_bf16_f32 v127, v14, v15
	v_mul_f32_e32 v128, 0x3fb8aa3b, v121
	v_exp_f32_e32 v128, v128
	global_store_dwordx4 v0, v[124:127], s[98:99]
	s_add_u32 s98, s98, 0x8100
	s_addc_u32 s99, s99, 0
	v_lshlrev_b32_e32 v130, 16, v96
	v_and_b32_e32 v131, 0xffff0000, v96
	v_lshlrev_b32_e32 v132, 16, v97
	v_and_b32_e32 v133, 0xffff0000, v97
	v_lshlrev_b32_e32 v134, 16, v98
	v_and_b32_e32 v135, 0xffff0000, v98
	v_lshlrev_b32_e32 v136, 16, v99
	v_and_b32_e32 v137, 0xffff0000, v99
	v_pk_fma_f32 v[8:9], v[8:9], v[128:129], v[130:131] op_sel_hi:[1,0,1]
	v_pk_fma_f32 v[10:11], v[10:11], v[128:129], v[132:133] op_sel_hi:[1,0,1]
	v_pk_fma_f32 v[12:13], v[12:13], v[128:129], v[134:135] op_sel_hi:[1,0,1]
	v_pk_fma_f32 v[14:15], v[14:15], v[128:129], v[136:137] op_sel_hi:[1,0,1]
	v_cvt_pk_bf16_f32 v124, v8, v9
	v_cvt_pk_bf16_f32 v125, v10, v11
	v_cvt_pk_bf16_f32 v126, v12, v13
	v_cvt_pk_bf16_f32 v127, v14, v15
	v_mul_f32_e32 v128, 0x3fb8aa3b, v122
	v_exp_f32_e32 v128, v128
	global_store_dwordx4 v0, v[124:127], s[98:99]
	s_add_u32 s98, s98, 0x8100
	s_addc_u32 s99, s99, 0
	v_lshlrev_b32_e32 v130, 16, v100
	v_and_b32_e32 v131, 0xffff0000, v100
	v_lshlrev_b32_e32 v132, 16, v101
	v_and_b32_e32 v133, 0xffff0000, v101
	v_lshlrev_b32_e32 v134, 16, v102
	v_and_b32_e32 v135, 0xffff0000, v102
	v_lshlrev_b32_e32 v136, 16, v103
	v_and_b32_e32 v137, 0xffff0000, v103
	v_pk_fma_f32 v[8:9], v[8:9], v[128:129], v[130:131] op_sel_hi:[1,0,1]
	v_pk_fma_f32 v[10:11], v[10:11], v[128:129], v[132:133] op_sel_hi:[1,0,1]
	v_pk_fma_f32 v[12:13], v[12:13], v[128:129], v[134:135] op_sel_hi:[1,0,1]
	v_pk_fma_f32 v[14:15], v[14:15], v[128:129], v[136:137] op_sel_hi:[1,0,1]
	v_cvt_pk_bf16_f32 v124, v8, v9
	v_cvt_pk_bf16_f32 v125, v10, v11
	v_cvt_pk_bf16_f32 v126, v12, v13
	v_cvt_pk_bf16_f32 v127, v14, v15
	v_mul_f32_e32 v128, 0x3fb8aa3b, v123
	v_exp_f32_e32 v128, v128
	global_store_dwordx4 v0, v[124:127], s[98:99]
	s_add_u32 s98, s98, 0x8100
	s_addc_u32 s99, s99, 0
	v_lshlrev_b32_e32 v130, 16, v104
	v_and_b32_e32 v131, 0xffff0000, v104
	v_lshlrev_b32_e32 v132, 16, v105
	v_and_b32_e32 v133, 0xffff0000, v105
	v_lshlrev_b32_e32 v134, 16, v106
	v_and_b32_e32 v135, 0xffff0000, v106
	v_lshlrev_b32_e32 v136, 16, v107
	v_and_b32_e32 v137, 0xffff0000, v107
	v_pk_fma_f32 v[8:9], v[8:9], v[128:129], v[130:131] op_sel_hi:[1,0,1]
	v_pk_fma_f32 v[10:11], v[10:11], v[128:129], v[132:133] op_sel_hi:[1,0,1]
	v_pk_fma_f32 v[12:13], v[12:13], v[128:129], v[134:135] op_sel_hi:[1,0,1]
	v_pk_fma_f32 v[14:15], v[14:15], v[128:129], v[136:137] op_sel_hi:[1,0,1]
	s_add_i32 s19, s19, s42
	s_cmpk_gt_i32 s19, 0x80
	s_cbranch_scc0 .LBB0_483
	s_waitcnt vmcnt(0)
	s_barrier
	s_mov_b64 s[98:99], exec
	v_readlane_b32 s100, v255, 1
	v_readlane_b32 s101, v255, 2
	s_nop 1
	s_mov_b64 exec, s[100:101]
	s_cbranch_execz .Lscan_sig_skip
	buffer_wbl2 sc1
	s_waitcnt vmcnt(0)
	v_readlane_b32 s100, v255, 5
	v_readlane_b32 s101, v255, 6
	v_mov_b32_e32 v217, 0x300
	v_mov_b32_e32 v230, 1
	s_nop 4
	global_atomic_add v217, v230, s[100:101]
